# static priority raise: every workgroup runs its pipelined GEMM K-loops at s_setprio 1 and drops to 0 for the epilogue (K-loop MFMA issue wins over the co-resident block's epilogue)
# baseline (speedup 1.0000x reference)
; template <int EPI, int MI>
; DI void gemm_tile(const GemmDesc& g, int tm, int tn, char* smem) {
;     ...
;   const int srow = tid >> 3;
;   const int schunk = (tid & 7) ^ ((srow & 7) ^ ((srow >> 3) & 3));
; template <int EPI, int MI>
; DI void gemm_phase(const GemmDesc& g, char* smem, int vb, int nvb) {
;     ...
;   for (int q = start; q < local; q += step) {
;     const int mg = q / per;
;     const int rem = q - mg * per;
;     const int tn = rem / PM;
;     const int tm = mbase + mg * PM + (rem - tn * PM);
.LBB0_202:
	s_abs_i32 s1, s5
	v_readlane_b32 s15, v219, 45
	s_mul_hi_u32 s15, s1, s15
	v_readlane_b32 s18, v219, 44
	s_mul_i32 s16, s15, s18
	s_sub_i32 s1, s1, s16
	s_ashr_i32 s0, s5, 31
	s_add_i32 s16, s15, 1
	s_sub_i32 s17, s1, s18
	s_cmp_ge_u32 s1, s18
	s_cselect_b32 s15, s16, s15
	s_cselect_b32 s1, s17, s1
	s_add_i32 s16, s15, 1
	s_cmp_ge_u32 s1, s18
	s_cselect_b32 s1, s16, s15
	s_xor_b32 s1, s1, s0
	s_sub_i32 s15, s1, s0
	s_mul_i32 s16, s15, s18
	s_sub_i32 s16, s5, s16
	s_abs_i32 s18, s16
	v_readlane_b32 s19, v219, 46
	s_mul_hi_u32 s19, s18, s19
	v_readlane_b32 s42, v218, 32
	s_mul_i32 s38, s19, s42
	s_sub_i32 s18, s18, s38
	s_ashr_i32 s17, s16, 31
	s_add_i32 s38, s19, 1
	s_sub_i32 s39, s18, s42
	s_cmp_ge_u32 s18, s42
	s_cselect_b32 s19, s38, s19
	s_cselect_b32 s18, s39, s18
	s_add_i32 s38, s19, 1
	s_cmp_ge_u32 s18, s42
	s_cselect_b32 s18, s38, s19
	s_xor_b32 s18, s18, s17
	s_sub_i32 s39, s18, s17
	s_sub_i32 s15, s15, s39
	v_mov_b32_e32 v4, v132
	s_mul_i32 s15, s15, s42
	s_add_i32 s16, s16, s54
	s_add_i32 s38, s16, s15
	v_ashrrev_i32_e32 v97, 3, v4
	v_ashrrev_i32_e32 v120, 7, v4
	v_bfe_u32 v0, v4, 6, 2
	v_xor_b32_e32 v1, v97, v4
	s_mulk_i32 s38, 0xc0
	v_and_b32_e32 v121, 31, v4
	v_bitop3_b32 v2, v1, v0, 7 bitop3:0x6c
	v_mul_lo_u32 v0, v120, s6
	v_and_b32_e32 v115, 7, v4
	v_or_b32_e32 v5, v0, v121
	v_lshrrev_b32_e32 v0, 3, v4
	s_waitcnt vmcnt(10)
	v_add_u32_e32 v98, s38, v97
	v_bfe_u32 v122, v4, 5, 1
	v_bitop3_b32 v0, v0, v115, 3 bitop3:0x6c
	v_ashrrev_i32_e32 v99, 31, v98
	v_xor_b32_e32 v6, v0, v122
	v_lshlrev_b64 v[0:1], 11, v[98:99]
	v_readlane_b32 s42, v223, 59
	v_lshlrev_b32_e32 v99, 4, v4
	v_readlane_b32 s43, v223, 60
	v_lshlrev_b32_e32 v100, 4, v2
	v_lshl_add_u32 v2, s39, 7, v97
	v_add_u32_e32 v124, 0, v99
	v_lshl_add_u64 v[0:1], s[42:43], 0, v[0:1]
	v_mov_b32_e32 v101, v96
	v_ashrrev_i32_e32 v3, 31, v2
	v_readfirstlane_b32 s15, v124
	v_add_u32_e32 v125, 0x1000, v124
	v_lshl_add_u64 v[0:1], v[0:1], 0, v[100:101]
	v_lshlrev_b64 v[2:3], 11, v[2:3]
	s_mov_b32 m0, s15
	s_mov_b64 s[42:43], 0x10000
	v_readfirstlane_b32 s15, v125
	v_add_u32_e32 v126, 0x2000, v124
	s_waitcnt vmcnt(9)
	v_lshl_add_u64 v[102:103], s[70:71], 0, v[2:3]
	global_load_lds_dwordx4 v[0:1], off
	v_lshl_add_u64 v[2:3], v[0:1], 0, s[42:43]
	s_mov_b32 m0, s15
	s_mov_b64 s[44:45], 0x20000
	v_readfirstlane_b32 s15, v126
	v_add_u32_e32 v127, 0x3000, v124
	global_load_lds_dwordx4 v[2:3], off
	v_lshl_add_u64 v[2:3], v[0:1], 0, s[44:45]
	s_mov_b32 m0, s15
	s_mov_b64 s[46:47], 0x30000
	v_readfirstlane_b32 s15, v127
	v_add_u32_e32 v128, 0x4000, v124
	global_load_lds_dwordx4 v[2:3], off
	v_lshl_add_u64 v[2:3], v[0:1], 0, s[46:47]
	s_mov_b32 m0, s15
	s_mov_b64 s[52:53], 0x40000
	v_readfirstlane_b32 s15, v128
	v_add_u32_e32 v129, 0x5000, v124
	global_load_lds_dwordx4 v[2:3], off
	v_lshl_add_u64 v[2:3], v[0:1], 0, s[52:53]
	s_mov_b32 m0, s15
	s_mov_b64 s[52:53], 0x50000
	v_readfirstlane_b32 s15, v129
	v_add_u32_e32 v130, 0xc000, v124
	global_load_lds_dwordx4 v[2:3], off
	v_lshl_add_u64 v[0:1], v[0:1], 0, s[52:53]
	s_mov_b32 m0, s15
	v_readfirstlane_b32 s15, v130
	v_add_u32_e32 v131, 0xd000, v124
	global_load_lds_dwordx4 v[0:1], off
	v_lshl_add_u64 v[0:1], v[102:103], 0, v[100:101]
	s_mov_b32 m0, s15
	v_readfirstlane_b32 s15, v131
	v_add_u32_e32 v153, 0xe000, v124
	global_load_lds_dwordx4 v[0:1], off
	v_lshl_add_u64 v[2:3], v[0:1], 0, s[42:43]
	s_mov_b32 m0, s15
	v_readfirstlane_b32 s15, v153
	v_add_u32_e32 v154, 0xf000, v124
	global_load_lds_dwordx4 v[2:3], off
	v_lshl_add_u64 v[2:3], v[0:1], 0, s[44:45]
	s_mov_b32 m0, s15
	v_readfirstlane_b32 s15, v154
	global_load_lds_dwordx4 v[2:3], off
	v_lshl_add_u64 v[0:1], v[0:1], 0, s[46:47]
	s_mov_b32 m0, s15
	s_mul_i32 s0, s0, 43
	global_load_lds_dwordx4 v[0:1], off
	s_add_i32 s17, s17, s0
	s_sub_i32 s0, s17, s18
	s_mul_i32 s1, s1, 43
	s_sub_i32 s0, s0, s1
	v_readlane_b32 s1, v218, 33
	v_bfe_u32 v123, v4, 6, 1
	v_lshlrev_b32_e32 v0, 7, v121
	s_mul_i32 s0, s1, s0
	v_lshl_or_b32 v0, v123, 13, v0
	s_add_i32 s0, s0, s4
	v_add_u32_e32 v156, 0, v0
	v_add_u32_e32 v158, s10, v0
	v_add_u32_e32 v0, s0, v97
	v_ashrrev_i32_e32 v1, 31, v0
	s_waitcnt vmcnt(0)
; template <int EPI, int MI>
; DI void gemm_tile(const GemmDesc& g, int tm, int tn, char* smem) {
;     ...
;   f32x16 acc[MI][2];
; #pragma unroll
;   for (int a = 0; a < MI; ++a)
; #pragma unroll
;     for (int b = 0; b < 2; ++b)
; #pragma unroll
;       for (int i = 0; i < 16; ++i) acc[a][b][i] = 0.f;
;   const int srow = tid >> 3;
;   const int schunk = (tid & 7) ^ ((srow & 7) ^ ((srow >> 3) & 3));
;     ...
;   const int rowA = wm * (32 * MI) + r, rowB = wn * 64 + r;
;   const int hk = hh ^ ((r & 7) ^ ((r >> 3) & 3));
;     ...
;   G_GLDS(0, 0);
;   asm volatile("s_waitcnt vmcnt(0)" ::: "memory");
;   __syncthreads();
	v_lshlrev_b64 v[0:1], 11, v[0:1]
	v_lshlrev_b32_e32 v157, 4, v6
	v_lshl_add_u64 v[104:105], s[70:71], 0, v[0:1]
	v_mov_b32_e32 v0, 0
	v_lshl_add_u32 v155, v5, 7, 0
	s_mov_b32 s15, 0
	v_mov_b32_e32 v1, v0
	v_mov_b32_e32 v2, v0
	v_mov_b32_e32 v3, v0
	v_mov_b32_e32 v4, v0
	v_mov_b32_e32 v5, v0
	v_mov_b32_e32 v6, v0
	v_mov_b32_e32 v7, v0
	v_mov_b32_e32 v8, v0
	v_mov_b32_e32 v9, v0
	v_mov_b32_e32 v10, v0
	v_mov_b32_e32 v11, v0
	v_mov_b32_e32 v12, v0
	v_mov_b32_e32 v13, v0
	v_mov_b32_e32 v14, v0
	v_mov_b32_e32 v15, v0
	v_mov_b32_e32 v16, v0
	v_mov_b32_e32 v17, v0
	v_mov_b32_e32 v18, v0
	v_mov_b32_e32 v19, v0
	v_mov_b32_e32 v20, v0
	v_mov_b32_e32 v21, v0
	v_mov_b32_e32 v22, v0
	v_mov_b32_e32 v23, v0
	v_mov_b32_e32 v24, v0
	v_mov_b32_e32 v25, v0
	v_mov_b32_e32 v26, v0
	v_mov_b32_e32 v27, v0
	v_mov_b32_e32 v28, v0
	v_mov_b32_e32 v29, v0
	v_mov_b32_e32 v30, v0
	v_mov_b32_e32 v31, v0
	v_mov_b32_e32 v32, v0
	v_mov_b32_e32 v33, v0
	v_mov_b32_e32 v34, v0
	v_mov_b32_e32 v35, v0
	v_mov_b32_e32 v36, v0
	v_mov_b32_e32 v37, v0
	v_mov_b32_e32 v38, v0
	v_mov_b32_e32 v39, v0
	v_mov_b32_e32 v40, v0
	v_mov_b32_e32 v41, v0
	v_mov_b32_e32 v42, v0
	v_mov_b32_e32 v43, v0
	v_mov_b32_e32 v44, v0
	v_mov_b32_e32 v45, v0
	v_mov_b32_e32 v46, v0
	v_mov_b32_e32 v47, v0
	v_mov_b32_e32 v48, v0
	s_waitcnt vmcnt(0)
	v_mov_b32_e32 v49, v0
	v_mov_b32_e32 v50, v0
	v_mov_b32_e32 v51, v0
	v_mov_b32_e32 v52, v0
	v_mov_b32_e32 v53, v0
	v_mov_b32_e32 v54, v0
	v_mov_b32_e32 v55, v0
	v_mov_b32_e32 v56, v0
	v_mov_b32_e32 v57, v0
	v_mov_b32_e32 v58, v0
	v_mov_b32_e32 v59, v0
	v_mov_b32_e32 v60, v0
	v_mov_b32_e32 v61, v0
	v_mov_b32_e32 v62, v0
	v_mov_b32_e32 v63, v0
	v_mov_b32_e32 v64, v0
	v_mov_b32_e32 v65, v0
	v_mov_b32_e32 v66, v0
	v_mov_b32_e32 v67, v0
	v_mov_b32_e32 v68, v0
	v_mov_b32_e32 v69, v0
	v_mov_b32_e32 v70, v0
	v_mov_b32_e32 v71, v0
	v_mov_b32_e32 v72, v0
	v_mov_b32_e32 v73, v0
	v_mov_b32_e32 v74, v0
	v_mov_b32_e32 v75, v0
	v_mov_b32_e32 v76, v0
	v_mov_b32_e32 v77, v0
	v_mov_b32_e32 v78, v0
	v_mov_b32_e32 v79, v0
	v_mov_b32_e32 v80, v0
	v_mov_b32_e32 v81, v0
	v_mov_b32_e32 v82, v0
	v_mov_b32_e32 v83, v0
	v_mov_b32_e32 v84, v0
	v_mov_b32_e32 v85, v0
	v_mov_b32_e32 v86, v0
	v_mov_b32_e32 v87, v0
	v_mov_b32_e32 v88, v0
	v_mov_b32_e32 v89, v0
	v_mov_b32_e32 v90, v0
	v_mov_b32_e32 v91, v0
	v_mov_b32_e32 v92, v0
	v_mov_b32_e32 v93, v0
	v_mov_b32_e32 v94, v0
	v_mov_b32_e32 v95, v0
	v_xor_b32_e32 v159, 32, v157
	v_xor_b32_e32 v160, 64, v157
	v_xor_b32_e32 v161, 0x60, v157
	s_mov_b64 s[18:19], 0x80
	s_mov_b64 s[42:43], 0x10080
	s_setprio 1
	v_add_u32_e32 v162, v155, v157
	v_add_u32_e32 v163, v155, v159
	v_add_u32_e32 v164, v155, v160
	v_add_u32_e32 v165, v155, v161
	v_add_u32_e32 v166, v156, v157
	v_add_u32_e32 v167, v156, v159
	v_add_u32_e32 v168, v156, v160
	v_add_u32_e32 v169, v156, v161
	v_add_u32_e32 v170, v158, v157
	v_add_u32_e32 v171, v158, v159
	v_add_u32_e32 v172, v158, v160
	v_add_u32_e32 v173, v158, v161
	v_lshl_add_u64 v[174:175], v[104:105], 0, v[100:101]
	v_lshl_add_u64 v[176:177], v[102:103], 0, v[100:101]
	v_readfirstlane_b32 s100, v124
	s_waitcnt vmcnt(0) lgkmcnt(0)
	s_barrier
	s_add_u32 m0, s100, 0x6000
	v_lshl_add_u64 v[106:107], v[174:175], 0, s[96:97]
	global_load_lds_dwordx4 v[106:107], off
	s_add_u32 m0, s100, 0x7000
	v_lshl_add_u64 v[106:107], v[174:175], 0, s[50:51]
	global_load_lds_dwordx4 v[106:107], off
	s_add_u32 m0, s100, 0x8000
	v_lshl_add_u64 v[106:107], v[174:175], 0, s[24:25]
	global_load_lds_dwordx4 v[106:107], off
	s_add_u32 m0, s100, 0x9000
	v_lshl_add_u64 v[106:107], v[174:175], 0, s[26:27]
	global_load_lds_dwordx4 v[106:107], off
	ds_read_b128 v[236:239], v166 offset:49152
	ds_read_b128 v[240:243], v166 offset:53248
	ds_read_b128 v[224:227], v162
	ds_read_b128 v[228:231], v162 offset:4096
	s_mov_b32 s15, 0

; template <int EPI, int MI>
; DI void gemm_tile(const GemmDesc& g, int tm, int tn, char* smem) {
;     ...
;   const int srow = tid >> 3;
;   const int schunk = (tid & 7) ^ ((srow & 7) ^ ((srow >> 3) & 3));
; template <int EPI, int MI>
; DI void gemm_phase(const GemmDesc& g, char* smem, int vb, int nvb) {
;     ...
;   for (int q = start; q < local; q += step) {
;     const int mg = q / per;
;     const int rem = q - mg * per;
;     const int tn = rem / PM;
;     const int tm = mbase + mg * PM + (rem - tn * PM);
.LBB0_254:
	s_abs_i32 s0, s42
	v_readlane_b32 s1, v219, 48
	s_mul_hi_u32 s1, s0, s1
	v_readlane_b32 s17, v219, 47
	s_mul_i32 s4, s1, s17
	s_sub_i32 s0, s0, s4
	s_ashr_i32 s15, s42, 31
	s_add_i32 s4, s1, 1
	s_sub_i32 s5, s0, s17
	s_cmp_ge_u32 s0, s17
	s_cselect_b32 s1, s4, s1
	s_cselect_b32 s0, s5, s0
	s_add_i32 s4, s1, 1
	s_cmp_ge_u32 s0, s17
	s_cselect_b32 s0, s4, s1
	s_xor_b32 s16, s0, s15
	s_sub_i32 s0, s16, s15
	s_mul_i32 s1, s0, s17
	s_sub_i32 s1, s42, s1
	s_abs_i32 s4, s1
	v_readlane_b32 s5, v219, 46
	s_mul_hi_u32 s5, s4, s5
	v_readlane_b32 s43, v218, 32
	s_mul_i32 s18, s5, s43
	s_sub_i32 s4, s4, s18
	s_ashr_i32 s17, s1, 31
	s_add_i32 s18, s5, 1
	s_sub_i32 s19, s4, s43
	s_cmp_ge_u32 s4, s43
	s_cselect_b32 s5, s18, s5
	s_cselect_b32 s4, s19, s4
	s_add_i32 s18, s5, 1
	s_cmp_ge_u32 s4, s43
	s_cselect_b32 s4, s18, s5
	s_xor_b32 s18, s4, s17
	v_mov_b32_e32 v97, v132
	s_sub_i32 s4, s18, s17
	s_mul_i32 s0, s0, s43
	v_ashrrev_i32_e32 v6, 3, v97
	s_mul_i32 s5, s4, s43
	s_waitcnt vmcnt(8)
	v_ashrrev_i32_e32 v109, 7, v97
	v_bfe_u32 v1, v97, 6, 2
	v_xor_b32_e32 v2, v6, v97
	s_add_i32 s0, s0, s54
	s_sub_i32 s1, s1, s5
	v_and_b32_e32 v108, 31, v97
	v_bitop3_b32 v2, v2, v1, 7 bitop3:0x6c
	v_mul_lo_u32 v1, v109, s6
	s_add_i32 s1, s0, s1
	s_lshl_b32 s0, s4, 7
	v_and_b32_e32 v0, 7, v97
	v_or_b32_e32 v7, v1, v108
	v_lshrrev_b32_e32 v1, 3, v97
	v_readlane_b32 s4, v221, 5
	s_mul_i32 s43, s1, 0xc0
	v_bfe_u32 v115, v97, 5, 1
	v_bitop3_b32 v0, v1, v0, 3 bitop3:0x6c
	v_readlane_b32 s5, v221, 6
	v_xor_b32_e32 v8, v0, v115
	v_add_u32_e32 v3, s43, v6
	v_mov_b64_e32 v[0:1], s[4:5]
	s_movk_i32 s19, 0x1600
	v_mad_i64_i32 v[0:1], s[4:5], v3, s19, v[0:1]
	v_readlane_b32 s4, v221, 10
	v_readlane_b32 s5, v221, 11
	v_lshlrev_b32_e32 v98, 4, v2
	v_add_u32_e32 v9, s0, v6
	v_mov_b64_e32 v[2:3], s[4:5]
	v_lshlrev_b32_e32 v120, 4, v97
	v_mad_i64_i32 v[2:3], s[4:5], v9, s19, v[2:3]
	v_add_u32_e32 v121, 0, v120
	v_mov_b32_e32 v99, v96
	v_readfirstlane_b32 s4, v121
	v_add_u32_e32 v122, 0x1000, v121
	v_lshl_add_u64 v[0:1], v[0:1], 0, v[98:99]
	s_mov_b32 m0, s4
	s_mov_b64 s[44:45], 0x2c000
	v_readfirstlane_b32 s4, v122
	v_add_u32_e32 v123, 0x2000, v121
	global_load_lds_dwordx4 v[0:1], off
	v_lshl_add_u64 v[4:5], v[0:1], 0, s[44:45]
	s_mov_b32 m0, s4
	s_mov_b64 s[46:47], 0x58000
	v_readfirstlane_b32 s4, v123
	v_add_u32_e32 v124, 0x3000, v121
	global_load_lds_dwordx4 v[4:5], off
	v_lshl_add_u64 v[4:5], v[0:1], 0, s[46:47]
	s_mov_b32 m0, s4
	s_mov_b64 s[52:53], 0x84000
	v_readfirstlane_b32 s4, v124
	global_load_lds_dwordx4 v[4:5], off
	v_lshl_add_u64 v[4:5], v[0:1], 0, s[52:53]
	s_mov_b32 m0, s4
	s_mov_b64 s[4:5], 0xb0000
	v_add_u32_e32 v125, 0x4000, v121
	global_load_lds_dwordx4 v[4:5], off
	v_lshl_add_u64 v[4:5], v[0:1], 0, s[4:5]
	v_readfirstlane_b32 s4, v125
	s_mov_b32 m0, s4
	s_mov_b64 s[4:5], 0xdc000
	v_add_u32_e32 v126, 0x5000, v121
	v_lshl_add_u64 v[0:1], v[0:1], 0, s[4:5]
	v_readfirstlane_b32 s4, v126
	v_add_u32_e32 v127, 0xc000, v121
	global_load_lds_dwordx4 v[4:5], off
	s_mov_b32 m0, s4
	v_readfirstlane_b32 s4, v127
	v_add_u32_e32 v128, 0xd000, v121
	global_load_lds_dwordx4 v[0:1], off
	v_lshl_add_u64 v[0:1], v[2:3], 0, v[98:99]
	s_mov_b32 m0, s4
	v_readfirstlane_b32 s4, v128
	v_add_u32_e32 v129, 0xe000, v121
	global_load_lds_dwordx4 v[0:1], off
	v_lshl_add_u64 v[2:3], v[0:1], 0, s[44:45]
	s_mov_b32 m0, s4
	v_readfirstlane_b32 s4, v129
	v_add_u32_e32 v130, 0xf000, v121
	global_load_lds_dwordx4 v[2:3], off
	v_lshl_add_u64 v[2:3], v[0:1], 0, s[46:47]
	s_mov_b32 m0, s4
	v_readfirstlane_b32 s4, v130
	global_load_lds_dwordx4 v[2:3], off
	v_lshl_add_u64 v[0:1], v[0:1], 0, s[52:53]
	s_mov_b32 m0, s4
	s_mul_i32 s15, s15, 7
	global_load_lds_dwordx4 v[0:1], off
	s_add_i32 s17, s17, s15
	s_sub_i32 s4, s17, s18
	s_mul_i32 s16, s16, 7
	s_sub_i32 s4, s4, s16
	v_readlane_b32 s5, v218, 33
	v_lshlrev_b32_e32 v0, 7, v97
	s_mul_i32 s4, s5, s4
	v_and_b32_e32 v0, 0x2f80, v0
	s_add_i32 s4, s4, s39
	s_waitcnt vmcnt(0)
; template <int EPI, int MI>
; DI void gemm_tile(const GemmDesc& g, int tm, int tn, char* smem) {
;     ...
;   f32x16 acc[MI][2];
; #pragma unroll
;   for (int a = 0; a < MI; ++a)
; #pragma unroll
;     for (int b = 0; b < 2; ++b)
; #pragma unroll
;       for (int i = 0; i < 16; ++i) acc[a][b][i] = 0.f;
;   const int srow = tid >> 3;
;   const int schunk = (tid & 7) ^ ((srow & 7) ^ ((srow >> 3) & 3));
;     ...
;   const int rowA = wm * (32 * MI) + r, rowB = wn * 64 + r;
;   const int hk = hh ^ ((r & 7) ^ ((r >> 3) & 3));
;     ...
;   G_GLDS(0, 0);
;   asm volatile("s_waitcnt vmcnt(0)" ::: "memory");
;   __syncthreads();
	v_add_u32_e32 v153, 0, v0
	v_add_u32_e32 v155, s10, v0
	v_add_u32_e32 v2, s4, v6
	v_mov_b64_e32 v[0:1], s[70:71]
	v_lshlrev_b32_e32 v154, 4, v8
	v_mad_i64_i32 v[100:101], s[4:5], v2, s19, v[0:1]
	v_mad_i64_i32 v[102:103], s[4:5], v9, s19, v[0:1]
	v_mov_b32_e32 v0, 0
	v_lshl_add_u32 v131, v7, 7, 0
	v_xor_b32_e32 v156, 32, v154
	v_xor_b32_e32 v157, 64, v154
	v_xor_b32_e32 v158, 0x60, v154
	s_mov_b32 s15, 0
	v_mov_b32_e32 v1, v0
	v_mov_b32_e32 v2, v0
	v_mov_b32_e32 v3, v0
	v_mov_b32_e32 v4, v0
	v_mov_b32_e32 v5, v0
	v_mov_b32_e32 v6, v0
	v_mov_b32_e32 v7, v0
	v_mov_b32_e32 v8, v0
	v_mov_b32_e32 v9, v0
	v_mov_b32_e32 v10, v0
	v_mov_b32_e32 v11, v0
	v_mov_b32_e32 v12, v0
	v_mov_b32_e32 v13, v0
	v_mov_b32_e32 v14, v0
	v_mov_b32_e32 v15, v0
	v_mov_b32_e32 v16, v0
	v_mov_b32_e32 v17, v0
	v_mov_b32_e32 v18, v0
	v_mov_b32_e32 v19, v0
	v_mov_b32_e32 v20, v0
	v_mov_b32_e32 v21, v0
	v_mov_b32_e32 v22, v0
	v_mov_b32_e32 v23, v0
	v_mov_b32_e32 v24, v0
	v_mov_b32_e32 v25, v0
	v_mov_b32_e32 v26, v0
	v_mov_b32_e32 v27, v0
	v_mov_b32_e32 v28, v0
	v_mov_b32_e32 v29, v0
	v_mov_b32_e32 v30, v0
	v_mov_b32_e32 v31, v0
	v_mov_b32_e32 v32, v0
	v_mov_b32_e32 v33, v0
	v_mov_b32_e32 v34, v0
	v_mov_b32_e32 v35, v0
	v_mov_b32_e32 v36, v0
	v_mov_b32_e32 v37, v0
	v_mov_b32_e32 v38, v0
	v_mov_b32_e32 v39, v0
	v_mov_b32_e32 v40, v0
	v_mov_b32_e32 v41, v0
	v_mov_b32_e32 v42, v0
	v_mov_b32_e32 v43, v0
	v_mov_b32_e32 v44, v0
	v_mov_b32_e32 v45, v0
	v_mov_b32_e32 v46, v0
	v_mov_b32_e32 v47, v0
	v_mov_b32_e32 v48, v0
	s_waitcnt vmcnt(0)
	v_mov_b32_e32 v49, v0
	v_mov_b32_e32 v50, v0
	v_mov_b32_e32 v51, v0
	v_mov_b32_e32 v52, v0
	v_mov_b32_e32 v53, v0
	v_mov_b32_e32 v54, v0
	v_mov_b32_e32 v55, v0
	v_mov_b32_e32 v56, v0
	v_mov_b32_e32 v57, v0
	v_mov_b32_e32 v58, v0
	v_mov_b32_e32 v59, v0
	v_mov_b32_e32 v60, v0
	v_mov_b32_e32 v61, v0
	v_mov_b32_e32 v62, v0
	v_mov_b32_e32 v63, v0
	v_mov_b32_e32 v64, v0
	v_mov_b32_e32 v65, v0
	v_mov_b32_e32 v66, v0
	v_mov_b32_e32 v67, v0
	v_mov_b32_e32 v68, v0
	v_mov_b32_e32 v69, v0
	v_mov_b32_e32 v70, v0
	v_mov_b32_e32 v71, v0
	v_mov_b32_e32 v72, v0
	v_mov_b32_e32 v73, v0
	v_mov_b32_e32 v74, v0
	v_mov_b32_e32 v75, v0
	v_mov_b32_e32 v76, v0
	v_mov_b32_e32 v77, v0
	v_mov_b32_e32 v78, v0
	v_mov_b32_e32 v79, v0
	v_mov_b32_e32 v80, v0
	v_mov_b32_e32 v81, v0
	v_mov_b32_e32 v82, v0
	v_mov_b32_e32 v83, v0
	v_mov_b32_e32 v84, v0
	v_mov_b32_e32 v85, v0
	v_mov_b32_e32 v86, v0
	v_mov_b32_e32 v87, v0
	v_mov_b32_e32 v88, v0
	v_mov_b32_e32 v89, v0
	v_mov_b32_e32 v90, v0
	v_mov_b32_e32 v91, v0
	v_mov_b32_e32 v92, v0
	v_mov_b32_e32 v93, v0
	v_mov_b32_e32 v94, v0
	v_mov_b32_e32 v95, v0
	s_setprio 1
	v_add_u32_e32 v162, v131, v154
	v_add_u32_e32 v163, v131, v156
	v_add_u32_e32 v164, v131, v157
	v_add_u32_e32 v165, v131, v158
	v_add_u32_e32 v166, v153, v154
	v_add_u32_e32 v167, v153, v156
	v_add_u32_e32 v168, v153, v157
	v_add_u32_e32 v169, v153, v158
	v_add_u32_e32 v170, v155, v154
	v_add_u32_e32 v171, v155, v156
	v_add_u32_e32 v172, v155, v157
	v_add_u32_e32 v173, v155, v158
	v_lshl_add_u64 v[252:253], v[100:101], 0, v[98:99]
	v_lshl_add_u64 v[254:255], v[102:103], 0, v[98:99]
	v_readfirstlane_b32 s100, v121
	s_mov_b64 s[4:5], 0x80
	s_waitcnt vmcnt(0) lgkmcnt(0)
	s_barrier
	s_mov_b64 s[16:17], 0x5872080
	s_add_u32 m0, s100, 0x6000
	v_lshl_add_u64 v[106:107], v[252:253], 0, s[16:17]
	global_load_lds_dwordx4 v[106:107], off
	s_mov_b64 s[16:17], 0x589e080
	s_add_u32 m0, s100, 0x7000
	v_lshl_add_u64 v[106:107], v[252:253], 0, s[16:17]
	global_load_lds_dwordx4 v[106:107], off
	s_mov_b64 s[16:17], 0x58ca080
	s_add_u32 m0, s100, 0x8000
	v_lshl_add_u64 v[106:107], v[252:253], 0, s[16:17]
	global_load_lds_dwordx4 v[106:107], off
	s_mov_b64 s[16:17], 0x58f6080
	s_add_u32 m0, s100, 0x9000
	v_lshl_add_u64 v[106:107], v[252:253], 0, s[16:17]
	global_load_lds_dwordx4 v[106:107], off
	s_mov_b64 s[16:17], 0x5922080
	s_add_u32 m0, s100, 0xa000
	v_lshl_add_u64 v[106:107], v[252:253], 0, s[16:17]
	global_load_lds_dwordx4 v[106:107], off
	s_mov_b64 s[16:17], 0x594e080
	s_add_u32 m0, s100, 0xb000
	v_lshl_add_u64 v[106:107], v[252:253], 0, s[16:17]
	global_load_lds_dwordx4 v[106:107], off
	v_lshl_add_u64 v[252:253], v[252:253], 0, s[4:5]
	s_mov_b64 s[16:17], 0x1600080
	s_add_u32 m0, s100, 0x10000
	v_lshl_add_u64 v[106:107], v[254:255], 0, s[16:17]
	global_load_lds_dwordx4 v[106:107], off
	s_mov_b64 s[16:17], 0x162c080
	s_add_u32 m0, s100, 0x11000
	v_lshl_add_u64 v[106:107], v[254:255], 0, s[16:17]
	global_load_lds_dwordx4 v[106:107], off
	s_mov_b64 s[16:17], 0x1658080
	s_add_u32 m0, s100, 0x12000
	v_lshl_add_u64 v[106:107], v[254:255], 0, s[16:17]
	global_load_lds_dwordx4 v[106:107], off
	s_mov_b64 s[16:17], 0x1684080
	s_add_u32 m0, s100, 0x13000
	v_lshl_add_u64 v[106:107], v[254:255], 0, s[16:17]
	global_load_lds_dwordx4 v[106:107], off
	v_lshl_add_u64 v[254:255], v[254:255], 0, s[4:5]
	ds_read_b128 v[236:239], v166 offset:49152
	ds_read_b128 v[240:243], v166 offset:53248
	ds_read_b128 v[224:227], v162
	ds_read_b128 v[228:231], v162 offset:4096
	s_mov_b32 s15, 0

; template <int EPI, int MI>
; DI void gemm_tile(const GemmDesc& g, int tm, int tn, char* smem) {
;     ...
;   const int srow = tid >> 3;
;   const int schunk = (tid & 7) ^ ((srow & 7) ^ ((srow >> 3) & 3));
; template <int EPI, int MI>
; DI void gemm_phase(const GemmDesc& g, char* smem, int vb, int nvb) {
;     ...
;   for (int q = start; q < local; q += step) {
;     const int mg = q / per;
;     const int rem = q - mg * per;
;     const int tn = rem / PM;
;     const int tm = mbase + mg * PM + (rem - tn * PM);
.LBB0_371:
	s_abs_i32 s1, s47
	s_mul_hi_u32 s4, s1, s45
	s_mul_i32 s5, s4, s43
	s_sub_i32 s1, s1, s5
	s_ashr_i32 s0, s47, 31
	s_add_i32 s5, s4, 1
	s_sub_i32 s15, s1, s43
	s_cmp_ge_u32 s1, s43
	s_cselect_b32 s4, s5, s4
	s_cselect_b32 s1, s15, s1
	s_add_i32 s5, s4, 1
	s_cmp_ge_u32 s1, s43
	s_cselect_b32 s1, s5, s4
	s_xor_b32 s1, s1, s0
	s_sub_i32 s4, s1, s0
	s_mul_i32 s5, s4, s43
	s_sub_i32 s5, s47, s5
	s_abs_i32 s16, s5
	v_readlane_b32 s17, v219, 46
	s_mul_hi_u32 s17, s16, s17
	v_readlane_b32 s38, v218, 32
	s_mul_i32 s18, s17, s38
	s_sub_i32 s16, s16, s18
	s_ashr_i32 s15, s5, 31
	s_add_i32 s18, s17, 1
	s_sub_i32 s19, s16, s38
	s_cmp_ge_u32 s16, s38
	s_cselect_b32 s17, s18, s17
	s_cselect_b32 s16, s19, s16
	s_add_i32 s18, s17, 1
	s_cmp_ge_u32 s16, s38
	s_cselect_b32 s16, s18, s17
	s_xor_b32 s16, s16, s15
	s_sub_i32 s17, s16, s15
	s_sub_i32 s18, s4, s17
	v_mov_b32_e32 v97, v132
	s_mul_i32 s18, s18, s38
	s_add_i32 s5, s5, s54
	s_add_i32 s48, s5, s18
	v_ashrrev_i32_e32 v0, 7, v97
	v_and_b32_e32 v1, 7, v97
	v_mul_lo_u32 v115, v0, s6
	v_lshrrev_b32_e32 v0, 3, v97
	s_mulk_i32 s48, 0xc0
	s_waitcnt vmcnt(8)
	v_bfe_u32 v109, v97, 5, 1
	v_ashrrev_i32_e32 v8, 3, v97
	v_bitop3_b32 v0, v0, v1, 3 bitop3:0x6c
	v_bfe_u32 v2, v97, 6, 2
	v_xor_b32_e32 v3, v8, v97
	v_xor_b32_e32 v10, v0, v109
	v_add_u32_e32 v0, s48, v8
	s_lshl_b32 s49, s17, 7
	v_bitop3_b32 v2, v3, v2, 7 bitop3:0x6c
	v_ashrrev_i32_e32 v1, 31, v0
	v_readlane_b32 s18, v223, 59
	v_lshlrev_b64 v[0:1], 11, v[0:1]
	v_readlane_b32 s19, v223, 60
	v_lshlrev_b32_e32 v98, 4, v2
	v_add_u32_e32 v2, s49, v8
	v_lshlrev_b32_e32 v120, 4, v97
	v_lshl_add_u64 v[0:1], s[18:19], 0, v[0:1]
	v_ashrrev_i32_e32 v3, 31, v2
	v_readlane_b32 s18, v221, 16
	v_add_u32_e32 v121, 0, v120
	v_mov_b32_e32 v99, v96
	v_lshlrev_b64 v[2:3], 11, v[2:3]
	v_readlane_b32 s19, v221, 17
	v_readfirstlane_b32 s5, v121
	v_add_u32_e32 v122, 0x1000, v121
	v_lshl_add_u64 v[0:1], v[0:1], 0, v[98:99]
	v_lshl_add_u64 v[4:5], s[18:19], 0, v[2:3]
	s_mov_b32 m0, s5
	s_mov_b64 s[18:19], 0x10000
	v_readfirstlane_b32 s5, v122
	v_add_u32_e32 v123, 0x2000, v121
	global_load_lds_dwordx4 v[0:1], off
	v_lshl_add_u64 v[6:7], v[0:1], 0, s[18:19]
	s_mov_b32 m0, s5
	s_mov_b64 s[38:39], 0x20000
	v_readfirstlane_b32 s5, v123
	v_add_u32_e32 v124, 0x3000, v121
	global_load_lds_dwordx4 v[6:7], off
	v_lshl_add_u64 v[6:7], v[0:1], 0, s[38:39]
	s_mov_b32 m0, s5
	s_mov_b64 s[52:53], 0x30000
	v_readfirstlane_b32 s5, v124
	v_add_u32_e32 v125, 0x4000, v121
	global_load_lds_dwordx4 v[6:7], off
	v_lshl_add_u64 v[6:7], v[0:1], 0, s[52:53]
	s_mov_b32 m0, s5
	s_mov_b64 s[72:73], 0x40000
	v_readfirstlane_b32 s5, v125
	v_add_u32_e32 v126, 0x5000, v121
	global_load_lds_dwordx4 v[6:7], off
	v_lshl_add_u64 v[6:7], v[0:1], 0, s[72:73]
	s_mov_b32 m0, s5
	s_mov_b64 s[72:73], 0x50000
	v_readfirstlane_b32 s5, v126
	v_add_u32_e32 v127, 0xc000, v121
	global_load_lds_dwordx4 v[6:7], off
	v_lshl_add_u64 v[0:1], v[0:1], 0, s[72:73]
	s_mov_b32 m0, s5
	v_readfirstlane_b32 s5, v127
	v_add_u32_e32 v128, 0xd000, v121
	global_load_lds_dwordx4 v[0:1], off
	v_lshl_add_u64 v[0:1], v[4:5], 0, v[98:99]
	s_mov_b32 m0, s5
	v_readfirstlane_b32 s5, v128
	v_add_u32_e32 v129, 0xe000, v121
	global_load_lds_dwordx4 v[0:1], off
	v_lshl_add_u64 v[4:5], v[0:1], 0, s[18:19]
	s_mov_b32 m0, s5
	v_readfirstlane_b32 s5, v129
	v_add_u32_e32 v130, 0xf000, v121
	global_load_lds_dwordx4 v[4:5], off
	v_lshl_add_u64 v[4:5], v[0:1], 0, s[38:39]
	s_mov_b32 m0, s5
	v_readfirstlane_b32 s5, v130
	global_load_lds_dwordx4 v[4:5], off
	v_lshl_add_u64 v[0:1], v[0:1], 0, s[52:53]
	s_mov_b32 m0, s5
	s_add_i32 s1, s1, s15
	global_load_lds_dwordx4 v[0:1], off
	s_mul_i32 s4, s20, s4
	s_sub_i32 s1, s1, s4
	s_sub_i32 s1, s1, s16
	s_sub_i32 s0, s1, s0
	v_readlane_b32 s1, v218, 33
	v_lshlrev_b32_e32 v0, 7, v97
	s_mul_i32 s0, s1, s0
	v_and_b32_e32 v0, 0x2f80, v0
	s_add_i32 s0, s0, s46
	v_add_u32_e32 v153, 0, v0
	v_add_u32_e32 v155, s10, v0
	v_add_u32_e32 v0, s0, v8
	v_ashrrev_i32_e32 v1, 31, v0
	v_and_b32_e32 v108, 31, v97
	s_waitcnt vmcnt(0)
; template <int EPI, int MI>
; DI void gemm_tile(const GemmDesc& g, int tm, int tn, char* smem) {
;     ...
;   f32x16 acc[MI][2];
; #pragma unroll
;   for (int a = 0; a < MI; ++a)
; #pragma unroll
;     for (int b = 0; b < 2; ++b)
; #pragma unroll
;       for (int i = 0; i < 16; ++i) acc[a][b][i] = 0.f;
;   const int srow = tid >> 3;
;   const int schunk = (tid & 7) ^ ((srow & 7) ^ ((srow >> 3) & 3));
;     ...
;   const int rowA = wm * (32 * MI) + r, rowB = wn * 64 + r;
;   const int hk = hh ^ ((r & 7) ^ ((r >> 3) & 3));
;     ...
;   G_GLDS(0, 0);
;   asm volatile("s_waitcnt vmcnt(0)" ::: "memory");
;   __syncthreads();
	v_lshlrev_b64 v[0:1], 11, v[0:1]
	v_or_b32_e32 v9, v115, v108
	v_lshlrev_b32_e32 v154, 4, v10
	v_lshl_add_u64 v[102:103], s[70:71], 0, v[0:1]
	v_mov_b32_e32 v0, 0
	v_lshl_add_u32 v131, v9, 7, 0
	v_xor_b32_e32 v156, 32, v154
	v_xor_b32_e32 v157, 64, v154
	v_xor_b32_e32 v158, 0x60, v154
	v_lshl_add_u64 v[100:101], s[70:71], 0, v[2:3]
	s_mov_b32 s4, 0
	v_mov_b32_e32 v1, v0
	v_mov_b32_e32 v2, v0
	v_mov_b32_e32 v3, v0
	v_mov_b32_e32 v4, v0
	v_mov_b32_e32 v5, v0
	v_mov_b32_e32 v6, v0
	v_mov_b32_e32 v7, v0
	v_mov_b32_e32 v8, v0
	v_mov_b32_e32 v9, v0
	v_mov_b32_e32 v10, v0
	v_mov_b32_e32 v11, v0
	v_mov_b32_e32 v12, v0
	v_mov_b32_e32 v13, v0
	v_mov_b32_e32 v14, v0
	v_mov_b32_e32 v15, v0
	v_mov_b32_e32 v16, v0
	v_mov_b32_e32 v17, v0
	v_mov_b32_e32 v18, v0
	v_mov_b32_e32 v19, v0
	v_mov_b32_e32 v20, v0
	v_mov_b32_e32 v21, v0
	v_mov_b32_e32 v22, v0
	v_mov_b32_e32 v23, v0
	v_mov_b32_e32 v24, v0
	v_mov_b32_e32 v25, v0
	v_mov_b32_e32 v26, v0
	v_mov_b32_e32 v27, v0
	v_mov_b32_e32 v28, v0
	v_mov_b32_e32 v29, v0
	v_mov_b32_e32 v30, v0
	v_mov_b32_e32 v31, v0
	v_mov_b32_e32 v32, v0
	v_mov_b32_e32 v33, v0
	v_mov_b32_e32 v34, v0
	v_mov_b32_e32 v35, v0
	v_mov_b32_e32 v36, v0
	v_mov_b32_e32 v37, v0
	v_mov_b32_e32 v38, v0
	v_mov_b32_e32 v39, v0
	v_mov_b32_e32 v40, v0
	v_mov_b32_e32 v41, v0
	v_mov_b32_e32 v42, v0
	v_mov_b32_e32 v43, v0
	v_mov_b32_e32 v44, v0
	v_mov_b32_e32 v45, v0
	v_mov_b32_e32 v46, v0
	v_mov_b32_e32 v47, v0
	v_mov_b32_e32 v48, v0
	s_waitcnt vmcnt(0)
	v_mov_b32_e32 v49, v0
	v_mov_b32_e32 v50, v0
	v_mov_b32_e32 v51, v0
	v_mov_b32_e32 v52, v0
	v_mov_b32_e32 v53, v0
	v_mov_b32_e32 v54, v0
	v_mov_b32_e32 v55, v0
	v_mov_b32_e32 v56, v0
	v_mov_b32_e32 v57, v0
	v_mov_b32_e32 v58, v0
	v_mov_b32_e32 v59, v0
	v_mov_b32_e32 v60, v0
	v_mov_b32_e32 v61, v0
	v_mov_b32_e32 v62, v0
	v_mov_b32_e32 v63, v0
	v_mov_b32_e32 v64, v0
	v_mov_b32_e32 v65, v0
	v_mov_b32_e32 v66, v0
	v_mov_b32_e32 v67, v0
	v_mov_b32_e32 v68, v0
	v_mov_b32_e32 v69, v0
	v_mov_b32_e32 v70, v0
	v_mov_b32_e32 v71, v0
	v_mov_b32_e32 v72, v0
	v_mov_b32_e32 v73, v0
	v_mov_b32_e32 v74, v0
	v_mov_b32_e32 v75, v0
	v_mov_b32_e32 v76, v0
	v_mov_b32_e32 v77, v0
	v_mov_b32_e32 v78, v0
	v_mov_b32_e32 v79, v0
	v_mov_b32_e32 v80, v0
	v_mov_b32_e32 v81, v0
	v_mov_b32_e32 v82, v0
	v_mov_b32_e32 v83, v0
	v_mov_b32_e32 v84, v0
	v_mov_b32_e32 v85, v0
	v_mov_b32_e32 v86, v0
	v_mov_b32_e32 v87, v0
	v_mov_b32_e32 v88, v0
	v_mov_b32_e32 v89, v0
	v_mov_b32_e32 v90, v0
	v_mov_b32_e32 v91, v0
	v_mov_b32_e32 v92, v0
	v_mov_b32_e32 v93, v0
	v_mov_b32_e32 v94, v0
	v_mov_b32_e32 v95, v0
	s_setprio 1
	v_add_u32_e32 v162, v131, v154
	v_add_u32_e32 v163, v131, v156
	v_add_u32_e32 v164, v131, v157
	v_add_u32_e32 v165, v131, v158
	v_add_u32_e32 v166, v153, v154
	v_add_u32_e32 v167, v153, v156
	v_add_u32_e32 v168, v153, v157
	v_add_u32_e32 v169, v153, v158
	v_add_u32_e32 v170, v155, v154
	v_add_u32_e32 v171, v155, v156
	v_add_u32_e32 v172, v155, v157
	v_add_u32_e32 v173, v155, v158
	v_lshl_add_u64 v[252:253], v[102:103], 0, v[98:99]
	v_lshl_add_u64 v[254:255], v[100:101], 0, v[98:99]
	v_readfirstlane_b32 s100, v121
	s_mov_b64 s[0:1], 0x80
	s_waitcnt vmcnt(0) lgkmcnt(0)
	s_barrier
	s_add_u32 m0, s100, 0x6000
	v_lshl_add_u64 v[106:107], v[252:253], 0, s[96:97]
	global_load_lds_dwordx4 v[106:107], off
	s_add_u32 m0, s100, 0x7000
	v_lshl_add_u64 v[106:107], v[252:253], 0, s[50:51]
	global_load_lds_dwordx4 v[106:107], off
	s_add_u32 m0, s100, 0x8000
	v_lshl_add_u64 v[106:107], v[252:253], 0, s[24:25]
	global_load_lds_dwordx4 v[106:107], off
	s_add_u32 m0, s100, 0x9000
	v_lshl_add_u64 v[106:107], v[252:253], 0, s[26:27]
	global_load_lds_dwordx4 v[106:107], off
	ds_read_b128 v[236:239], v166 offset:49152
	ds_read_b128 v[240:243], v166 offset:53248
	ds_read_b128 v[224:227], v162
	ds_read_b128 v[228:231], v162 offset:4096
	s_mov_b32 s101, 0

; template <int EPI, int MI>
; DI void gemm_tile(const GemmDesc& g, int tm, int tn, char* smem) {
;     ...
;   const int m0 = tm * BM, n0 = tn * 128;
;   const int nk = g.K >> 6;
;   f32x16 acc[MI][2];
; #pragma unroll
;   for (int a = 0; a < MI; ++a)
; #pragma unroll
;     for (int b = 0; b < 2; ++b)
; #pragma unroll
;       for (int i = 0; i < 16; ++i) acc[a][b][i] = 0.f;
;   const int srow = tid >> 3;
;   const int schunk = (tid & 7) ^ ((srow & 7) ^ ((srow >> 3) & 3));
;     ...
;   const int rowA = wm * (32 * MI) + r, rowB = wn * 64 + r;
;   const int hk = hh ^ ((r & 7) ^ ((r >> 3) & 3));
;     ...
;   G_GLDS(0, 0);
;   asm volatile("s_waitcnt vmcnt(0)" ::: "memory");
;   __syncthreads();
;   for (int kt = 0; kt < nk; kt += 2) {
;     if (kt + 1 < nk) G_GLDS(kt + 1, 1);
; template <int EPI, int MI>
; DI void gemm_phase(const GemmDesc& g, char* smem, int vb, int nvb) {
;     ...
;   for (int q = start; q < local; q += step) {
;     const int mg = q / per;
;     const int rem = q - mg * per;
;     const int tn = rem / PM;
;     const int tm = mbase + mg * PM + (rem - tn * PM);
.LBB0_1410:
	s_abs_i32 s1, s39
	s_mul_hi_u32 s40, s1, s17
	s_mul_i32 s41, s40, s15
	s_sub_i32 s1, s1, s41
	s_ashr_i32 s0, s39, 31
	s_add_i32 s41, s40, 1
	s_sub_i32 s42, s1, s15
	s_cmp_ge_u32 s1, s15
	s_cselect_b32 s40, s41, s40
	s_cselect_b32 s1, s42, s1
	s_add_i32 s41, s40, 1
	s_cmp_ge_u32 s1, s15
	s_cselect_b32 s1, s41, s40
	s_xor_b32 s1, s1, s0
	s_sub_i32 s40, s1, s0
	s_mul_i32 s41, s40, s15
	s_sub_i32 s42, s39, s41
	s_abs_i32 s41, s42
	s_mul_hi_u32 s44, s41, s18
	s_mul_i32 s45, s44, s4
	s_sub_i32 s41, s41, s45
	s_ashr_i32 s43, s42, 31
	s_add_i32 s45, s44, 1
	s_sub_i32 s46, s41, s4
	s_cmp_ge_u32 s41, s4
	s_cselect_b32 s44, s45, s44
	s_cselect_b32 s41, s46, s41
	s_add_i32 s45, s44, 1
	s_cmp_ge_u32 s41, s4
	s_cselect_b32 s41, s45, s44
	s_xor_b32 s44, s41, s43
	s_sub_i32 s41, s44, s43
	s_sub_i32 s40, s40, s41
	v_mov_b32_e32 v6, v132
	s_mul_i32 s40, s40, s4
	s_add_i32 s42, s42, s16
	s_add_i32 s42, s42, s40
	v_ashrrev_i32_e32 v76, 3, v6
	v_bfe_u32 v0, v6, 6, 2
	v_xor_b32_e32 v1, v76, v6
	s_lshl_b32 s40, s42, 7
	v_bitop3_b32 v2, v1, v0, 7 bitop3:0x6c
	v_ashrrev_i32_e32 v0, 1, v6
	v_and_b32_e32 v77, 7, v6
	v_and_b32_e32 v79, 0xffffffc0, v0
	v_lshrrev_b32_e32 v0, 3, v6
	v_add_u32_e32 v64, s40, v76
	v_bfe_u32 v78, v6, 5, 1
	v_bitop3_b32 v0, v0, v77, 3 bitop3:0x6c
	v_ashrrev_i32_e32 v65, 31, v64
	v_readlane_b32 s46, v223, 59
	v_and_b32_e32 v80, 31, v6
	v_bfe_u32 v81, v6, 6, 1
	v_xor_b32_e32 v9, v0, v78
	v_lshlrev_b64 v[0:1], 11, v[64:65]
	v_readlane_b32 s47, v223, 60
	v_lshlrev_b32_e32 v66, 4, v2
	v_lshl_add_u32 v2, s41, 7, v76
	v_lshlrev_b32_e32 v6, 4, v6
	v_lshl_add_u64 v[0:1], s[46:47], 0, v[0:1]
	v_ashrrev_i32_e32 v3, 31, v2
	v_readlane_b32 s46, v220, 54
	v_add_u32_e32 v65, 0, v6
	v_mov_b32_e32 v67, v96
	v_lshlrev_b64 v[2:3], 11, v[2:3]
	v_readlane_b32 s47, v220, 55
	v_readfirstlane_b32 s42, v65
	v_add_u32_e32 v82, 0x1000, v65
	v_lshl_add_u64 v[0:1], v[0:1], 0, v[66:67]
	v_lshl_add_u64 v[4:5], s[46:47], 0, v[2:3]
	s_mov_b32 m0, s42
	s_mov_b64 s[46:47], 0x10000
	v_readfirstlane_b32 s42, v82
	v_add_u32_e32 v83, 0x2000, v65
	global_load_lds_dwordx4 v[0:1], off
	v_lshl_add_u64 v[6:7], v[0:1], 0, s[46:47]
	s_mov_b32 m0, s42
	s_mov_b64 s[52:53], 0x20000
	v_readfirstlane_b32 s42, v83
	v_add_u32_e32 v84, 0x3000, v65
	global_load_lds_dwordx4 v[6:7], off
	v_lshl_add_u64 v[6:7], v[0:1], 0, s[52:53]
	s_mov_b32 m0, s42
	s_mov_b64 s[72:73], 0x30000
	v_readfirstlane_b32 s42, v84
	v_add_u32_e32 v85, 0x8000, v65
	global_load_lds_dwordx4 v[6:7], off
	v_lshl_add_u64 v[0:1], v[0:1], 0, s[72:73]
	s_mov_b32 m0, s42
	v_readfirstlane_b32 s42, v85
	v_add_u32_e32 v86, 0x9000, v65
	global_load_lds_dwordx4 v[0:1], off
	v_lshl_add_u64 v[0:1], v[4:5], 0, v[66:67]
	s_mov_b32 m0, s42
	v_readfirstlane_b32 s42, v86
	v_add_u32_e32 v87, 0xa000, v65
	global_load_lds_dwordx4 v[0:1], off
	v_lshl_add_u64 v[4:5], v[0:1], 0, s[46:47]
	s_mov_b32 m0, s42
	v_readfirstlane_b32 s42, v87
	v_add_u32_e32 v88, 0xb000, v65
	global_load_lds_dwordx4 v[4:5], off
	v_lshl_add_u64 v[4:5], v[0:1], 0, s[52:53]
	s_mov_b32 m0, s42
	v_readfirstlane_b32 s42, v88
	global_load_lds_dwordx4 v[4:5], off
	v_lshl_add_u64 v[0:1], v[0:1], 0, s[72:73]
	s_mov_b32 m0, s42
	s_mul_i32 s0, s0, 43
	global_load_lds_dwordx4 v[0:1], off
	s_add_i32 s43, s43, s0
	s_sub_i32 s0, s43, s44
	s_mul_i32 s1, s1, 43
	s_sub_i32 s0, s0, s1
	v_lshlrev_b32_e32 v0, 7, v80
	s_mul_i32 s0, s38, s0
	v_lshl_or_b32 v0, v81, 13, v0
	s_add_i32 s0, s0, s19
	v_add_u32_e32 v90, 0, v0
	v_add_u32_e32 v0, s0, v76
	v_ashrrev_i32_e32 v1, 31, v0
	s_waitcnt vmcnt(0)
	v_lshlrev_b64 v[0:1], 11, v[0:1]
	v_or_b32_e32 v8, v79, v80
	v_lshlrev_b32_e32 v91, 4, v9
	v_lshl_add_u64 v[68:69], s[70:71], 0, v[0:1]
	v_mov_b32_e32 v0, 0
	v_lshl_add_u32 v89, v8, 7, 0
	v_xor_b32_e32 v92, 32, v91
	v_xor_b32_e32 v93, 64, v91
	v_xor_b32_e32 v94, 0x60, v91
	v_lshl_add_u64 v[70:71], s[70:71], 0, v[2:3]
	s_mov_b32 s42, 0
	v_mov_b32_e32 v1, v0
	v_mov_b32_e32 v2, v0
	v_mov_b32_e32 v3, v0
	v_mov_b32_e32 v4, v0
	v_mov_b32_e32 v5, v0
	v_mov_b32_e32 v6, v0
	v_mov_b32_e32 v7, v0
	v_mov_b32_e32 v8, v0
	v_mov_b32_e32 v9, v0
	v_mov_b32_e32 v10, v0
	v_mov_b32_e32 v11, v0
	v_mov_b32_e32 v12, v0
	v_mov_b32_e32 v13, v0
	v_mov_b32_e32 v14, v0
	v_mov_b32_e32 v15, v0
	v_mov_b32_e32 v16, v0
	v_mov_b32_e32 v17, v0
	v_mov_b32_e32 v18, v0
	v_mov_b32_e32 v19, v0
	v_mov_b32_e32 v20, v0
	v_mov_b32_e32 v21, v0
	v_mov_b32_e32 v22, v0
	v_mov_b32_e32 v23, v0
	v_mov_b32_e32 v24, v0
	v_mov_b32_e32 v25, v0
	v_mov_b32_e32 v26, v0
	v_mov_b32_e32 v27, v0
	v_mov_b32_e32 v28, v0
	v_mov_b32_e32 v29, v0
	v_mov_b32_e32 v30, v0
	v_mov_b32_e32 v31, v0
	v_mov_b32_e32 v32, v0
	v_mov_b32_e32 v33, v0
	v_mov_b32_e32 v34, v0
	v_mov_b32_e32 v35, v0
	v_mov_b32_e32 v36, v0
	v_mov_b32_e32 v37, v0
	v_mov_b32_e32 v38, v0
	v_mov_b32_e32 v39, v0
	v_mov_b32_e32 v40, v0
	v_mov_b32_e32 v41, v0
	v_mov_b32_e32 v42, v0
	v_mov_b32_e32 v43, v0
	v_mov_b32_e32 v44, v0
	v_mov_b32_e32 v45, v0
	v_mov_b32_e32 v46, v0
	v_mov_b32_e32 v47, v0
	v_mov_b32_e32 v48, v0
	v_mov_b32_e32 v49, v0
	v_mov_b32_e32 v50, v0
	v_mov_b32_e32 v51, v0
	v_mov_b32_e32 v52, v0
	v_mov_b32_e32 v53, v0
	v_mov_b32_e32 v54, v0
	v_mov_b32_e32 v55, v0
	v_mov_b32_e32 v56, v0
	v_mov_b32_e32 v57, v0
	v_mov_b32_e32 v58, v0
	v_mov_b32_e32 v59, v0
	v_mov_b32_e32 v60, v0
	v_mov_b32_e32 v61, v0
	v_mov_b32_e32 v62, v0
	v_mov_b32_e32 v63, v0
	s_setprio 1
	v_add_u32_e32 v98, v89, v91
	v_add_u32_e32 v99, v89, v92
	v_add_u32_e32 v100, v89, v93
	v_add_u32_e32 v101, v89, v94
	v_add_u32_e32 v102, v90, v91
	v_add_u32_e32 v103, v90, v92
	v_add_u32_e32 v104, v90, v93
	v_add_u32_e32 v105, v90, v94
	v_lshl_add_u64 v[72:73], v[68:69], 0, v[66:67]
	v_lshl_add_u64 v[74:75], v[70:71], 0, v[66:67]
	v_readfirstlane_b32 s100, v65
	s_mov_b64 s[44:45], 0x80
	s_waitcnt vmcnt(0) lgkmcnt(0)
	s_barrier
	s_add_u32 m0, s100, 0x4000
	v_lshl_add_u64 v[106:107], v[72:73], 0, s[96:97]
	global_load_lds_dwordx4 v[106:107], off
	s_add_u32 m0, s100, 0x5000
	v_lshl_add_u64 v[106:107], v[72:73], 0, s[50:51]
	global_load_lds_dwordx4 v[106:107], off
	s_add_u32 m0, s100, 0x6000
	v_lshl_add_u64 v[106:107], v[72:73], 0, s[24:25]
	global_load_lds_dwordx4 v[106:107], off
	s_add_u32 m0, s100, 0x7000
	v_lshl_add_u64 v[106:107], v[72:73], 0, s[26:27]
	global_load_lds_dwordx4 v[106:107], off
	v_lshl_add_u64 v[72:73], v[72:73], 0, s[44:45]
	ds_read_b128 v[240:243], v102 offset:32768
	ds_read_b128 v[244:247], v102 offset:36864
	ds_read_b128 v[224:227], v98
	ds_read_b128 v[228:231], v98 offset:4096
	s_mov_b32 s101, 0

; template <int EPI, int MI>
; DI void gemm_tile(const GemmDesc& g, int tm, int tn, char* smem) {
;     ...
;   const int srow = tid >> 3;
;   const int schunk = (tid & 7) ^ ((srow & 7) ^ ((srow >> 3) & 3));
; template <int EPI, int MI>
; DI void gemm_phase(const GemmDesc& g, char* smem, int vb, int nvb) {
;     ...
;   for (int q = start; q < local; q += step) {
;     const int mg = q / per;
;     const int rem = q - mg * per;
;     const int tn = rem / PM;
;     const int tm = mbase + mg * PM + (rem - tn * PM);
.LBB0_1421:
	s_abs_i32 s1, s5
	v_readlane_b32 s15, v219, 45
	s_mul_hi_u32 s15, s1, s15
	v_readlane_b32 s18, v219, 44
	s_mul_i32 s16, s15, s18
	s_sub_i32 s1, s1, s16
	s_ashr_i32 s0, s5, 31
	s_add_i32 s16, s15, 1
	s_sub_i32 s17, s1, s18
	s_cmp_ge_u32 s1, s18
	s_cselect_b32 s15, s16, s15
	s_cselect_b32 s1, s17, s1
	s_add_i32 s16, s15, 1
	s_cmp_ge_u32 s1, s18
	s_cselect_b32 s1, s16, s15
	s_xor_b32 s1, s1, s0
	s_sub_i32 s15, s1, s0
	s_mul_i32 s16, s15, s18
	s_sub_i32 s16, s5, s16
	s_abs_i32 s18, s16
	v_readlane_b32 s19, v219, 46
	s_mul_hi_u32 s19, s18, s19
	v_readlane_b32 s40, v218, 32
	s_mul_i32 s38, s19, s40
	s_sub_i32 s18, s18, s38
	s_ashr_i32 s17, s16, 31
	s_add_i32 s38, s19, 1
	s_sub_i32 s39, s18, s40
	s_cmp_ge_u32 s18, s40
	s_cselect_b32 s19, s38, s19
	s_cselect_b32 s18, s39, s18
	s_add_i32 s38, s19, 1
	s_cmp_ge_u32 s18, s40
	s_cselect_b32 s18, s38, s19
	s_xor_b32 s18, s18, s17
	s_sub_i32 s39, s18, s17
	s_sub_i32 s15, s15, s39
	v_mov_b32_e32 v6, v132
	s_mul_i32 s15, s15, s40
	s_add_i32 s16, s16, s54
	s_add_i32 s38, s16, s15
	v_ashrrev_i32_e32 v97, 3, v6
	v_ashrrev_i32_e32 v120, 7, v6
	v_bfe_u32 v0, v6, 6, 2
	v_xor_b32_e32 v1, v97, v6
	s_mulk_i32 s38, 0xc0
	v_and_b32_e32 v121, 31, v6
	v_bitop3_b32 v2, v1, v0, 7 bitop3:0x6c
	v_mul_lo_u32 v0, v120, s6
	v_and_b32_e32 v115, 7, v6
	v_or_b32_e32 v8, v0, v121
	v_lshrrev_b32_e32 v0, 3, v6
	s_waitcnt vmcnt(10)
	v_add_u32_e32 v98, s38, v97
	v_bfe_u32 v122, v6, 5, 1
	v_bitop3_b32 v0, v0, v115, 3 bitop3:0x6c
	v_ashrrev_i32_e32 v99, 31, v98
	v_readlane_b32 s40, v223, 59
	v_xor_b32_e32 v9, v0, v122
	v_lshlrev_b64 v[0:1], 11, v[98:99]
	v_readlane_b32 s41, v223, 60
	v_lshlrev_b32_e32 v100, 4, v2
	v_lshl_add_u32 v2, s39, 7, v97
	v_lshlrev_b32_e32 v99, 4, v6
	v_lshl_add_u64 v[0:1], s[40:41], 0, v[0:1]
	v_ashrrev_i32_e32 v3, 31, v2
	v_readlane_b32 s40, v220, 54
	v_add_u32_e32 v124, 0, v99
	v_mov_b32_e32 v101, v96
	v_lshlrev_b64 v[2:3], 11, v[2:3]
	v_readlane_b32 s41, v220, 55
	v_readfirstlane_b32 s15, v124
	v_add_u32_e32 v125, 0x1000, v124
	v_lshl_add_u64 v[0:1], v[0:1], 0, v[100:101]
	v_lshl_add_u64 v[4:5], s[40:41], 0, v[2:3]
	s_mov_b32 m0, s15
	s_mov_b64 s[40:41], 0x10000
	v_readfirstlane_b32 s15, v125
	v_add_u32_e32 v126, 0x2000, v124
	v_bfe_u32 v123, v6, 6, 1
	global_load_lds_dwordx4 v[0:1], off
	v_lshl_add_u64 v[6:7], v[0:1], 0, s[40:41]
	s_mov_b32 m0, s15
	s_mov_b64 s[42:43], 0x20000
	v_readfirstlane_b32 s15, v126
	v_add_u32_e32 v127, 0x3000, v124
	global_load_lds_dwordx4 v[6:7], off
	v_lshl_add_u64 v[6:7], v[0:1], 0, s[42:43]
	s_mov_b32 m0, s15
	s_mov_b64 s[44:45], 0x30000
	v_readfirstlane_b32 s15, v127
	v_add_u32_e32 v128, 0x4000, v124
	global_load_lds_dwordx4 v[6:7], off
	v_lshl_add_u64 v[6:7], v[0:1], 0, s[44:45]
	s_mov_b32 m0, s15
	s_mov_b64 s[46:47], 0x40000
	v_readfirstlane_b32 s15, v128
	v_add_u32_e32 v129, 0x5000, v124
	global_load_lds_dwordx4 v[6:7], off
	v_lshl_add_u64 v[6:7], v[0:1], 0, s[46:47]
	s_mov_b32 m0, s15
	s_mov_b64 s[46:47], 0x50000
	v_readfirstlane_b32 s15, v129
	v_add_u32_e32 v130, 0xc000, v124
	global_load_lds_dwordx4 v[6:7], off
	v_lshl_add_u64 v[0:1], v[0:1], 0, s[46:47]
	s_mov_b32 m0, s15
	v_readfirstlane_b32 s15, v130
	v_add_u32_e32 v131, 0xd000, v124
	global_load_lds_dwordx4 v[0:1], off
	v_lshl_add_u64 v[0:1], v[4:5], 0, v[100:101]
	s_mov_b32 m0, s15
	v_readfirstlane_b32 s15, v131
	v_add_u32_e32 v153, 0xe000, v124
	global_load_lds_dwordx4 v[0:1], off
	v_lshl_add_u64 v[4:5], v[0:1], 0, s[40:41]
	s_mov_b32 m0, s15
	v_readfirstlane_b32 s15, v153
	v_add_u32_e32 v154, 0xf000, v124
	global_load_lds_dwordx4 v[4:5], off
	v_lshl_add_u64 v[4:5], v[0:1], 0, s[42:43]
	s_mov_b32 m0, s15
	v_readfirstlane_b32 s15, v154
	global_load_lds_dwordx4 v[4:5], off
	v_lshl_add_u64 v[0:1], v[0:1], 0, s[44:45]
	s_mov_b32 m0, s15
	s_mul_i32 s0, s0, 43
	global_load_lds_dwordx4 v[0:1], off
	s_add_i32 s17, s17, s0
	s_sub_i32 s0, s17, s18
	s_mul_i32 s1, s1, 43
	s_sub_i32 s0, s0, s1
	v_readlane_b32 s1, v218, 33
	v_lshlrev_b32_e32 v0, 7, v121
	s_mul_i32 s0, s1, s0
	v_lshl_or_b32 v0, v123, 13, v0
	s_add_i32 s0, s0, s4
	v_add_u32_e32 v156, 0, v0
	v_add_u32_e32 v158, s10, v0
	v_add_u32_e32 v0, s0, v97
	v_ashrrev_i32_e32 v1, 31, v0
	s_waitcnt vmcnt(0)
	v_lshlrev_b64 v[0:1], 11, v[0:1]
	v_lshlrev_b32_e32 v157, 4, v9
	s_waitcnt vmcnt(0)
; template <int EPI, int MI>
; DI void gemm_tile(const GemmDesc& g, int tm, int tn, char* smem) {
;     ...
;   f32x16 acc[MI][2];
; #pragma unroll
;   for (int a = 0; a < MI; ++a)
; #pragma unroll
;     for (int b = 0; b < 2; ++b)
; #pragma unroll
;       for (int i = 0; i < 16; ++i) acc[a][b][i] = 0.f;
;   const int srow = tid >> 3;
;   const int schunk = (tid & 7) ^ ((srow & 7) ^ ((srow >> 3) & 3));
;     ...
;   const int rowA = wm * (32 * MI) + r, rowB = wn * 64 + r;
;   const int hk = hh ^ ((r & 7) ^ ((r >> 3) & 3));
;     ...
;   G_GLDS(0, 0);
;   asm volatile("s_waitcnt vmcnt(0)" ::: "memory");
;   __syncthreads();
;   for (int kt = 0; kt < nk; kt += 2) {
;     if (kt + 1 < nk) G_GLDS(kt + 1, 1);
	v_lshl_add_u64 v[102:103], s[70:71], 0, v[0:1]
	v_mov_b32_e32 v0, 0
	v_lshl_add_u32 v155, v8, 7, 0
	v_xor_b32_e32 v159, 32, v157
	v_xor_b32_e32 v160, 64, v157
	v_xor_b32_e32 v161, 0x60, v157
	v_lshl_add_u64 v[104:105], s[70:71], 0, v[2:3]
	s_mov_b32 s15, 0
	v_mov_b32_e32 v1, v0
	v_mov_b32_e32 v2, v0
	v_mov_b32_e32 v3, v0
	v_mov_b32_e32 v4, v0
	v_mov_b32_e32 v5, v0
	v_mov_b32_e32 v6, v0
	v_mov_b32_e32 v7, v0
	v_mov_b32_e32 v8, v0
	v_mov_b32_e32 v9, v0
	v_mov_b32_e32 v10, v0
	v_mov_b32_e32 v11, v0
	v_mov_b32_e32 v12, v0
	v_mov_b32_e32 v13, v0
	v_mov_b32_e32 v14, v0
	v_mov_b32_e32 v15, v0
	v_mov_b32_e32 v16, v0
	v_mov_b32_e32 v17, v0
	v_mov_b32_e32 v18, v0
	v_mov_b32_e32 v19, v0
	v_mov_b32_e32 v20, v0
	v_mov_b32_e32 v21, v0
	v_mov_b32_e32 v22, v0
	v_mov_b32_e32 v23, v0
	v_mov_b32_e32 v24, v0
	v_mov_b32_e32 v25, v0
	v_mov_b32_e32 v26, v0
	v_mov_b32_e32 v27, v0
	v_mov_b32_e32 v28, v0
	v_mov_b32_e32 v29, v0
	v_mov_b32_e32 v30, v0
	v_mov_b32_e32 v31, v0
	v_mov_b32_e32 v32, v0
	v_mov_b32_e32 v33, v0
	v_mov_b32_e32 v34, v0
	v_mov_b32_e32 v35, v0
	v_mov_b32_e32 v36, v0
	v_mov_b32_e32 v37, v0
	v_mov_b32_e32 v38, v0
	v_mov_b32_e32 v39, v0
	v_mov_b32_e32 v40, v0
	v_mov_b32_e32 v41, v0
	v_mov_b32_e32 v42, v0
	v_mov_b32_e32 v43, v0
	v_mov_b32_e32 v44, v0
	v_mov_b32_e32 v45, v0
	v_mov_b32_e32 v46, v0
	v_mov_b32_e32 v47, v0
	v_mov_b32_e32 v48, v0
	v_mov_b32_e32 v49, v0
	v_mov_b32_e32 v50, v0
	v_mov_b32_e32 v51, v0
	v_mov_b32_e32 v52, v0
	v_mov_b32_e32 v53, v0
	v_mov_b32_e32 v54, v0
	v_mov_b32_e32 v55, v0
	v_mov_b32_e32 v56, v0
	v_mov_b32_e32 v57, v0
	v_mov_b32_e32 v58, v0
	v_mov_b32_e32 v59, v0
	v_mov_b32_e32 v60, v0
	v_mov_b32_e32 v61, v0
	v_mov_b32_e32 v62, v0
	v_mov_b32_e32 v63, v0
	v_mov_b32_e32 v64, v0
	v_mov_b32_e32 v65, v0
	v_mov_b32_e32 v66, v0
	v_mov_b32_e32 v67, v0
	v_mov_b32_e32 v68, v0
	v_mov_b32_e32 v69, v0
	v_mov_b32_e32 v70, v0
	v_mov_b32_e32 v71, v0
	v_mov_b32_e32 v72, v0
	v_mov_b32_e32 v73, v0
	v_mov_b32_e32 v74, v0
	v_mov_b32_e32 v75, v0
	v_mov_b32_e32 v76, v0
	v_mov_b32_e32 v77, v0
	v_mov_b32_e32 v78, v0
	v_mov_b32_e32 v79, v0
	v_mov_b32_e32 v80, v0
	v_mov_b32_e32 v81, v0
	v_mov_b32_e32 v82, v0
	v_mov_b32_e32 v83, v0
	v_mov_b32_e32 v84, v0
	v_mov_b32_e32 v85, v0
	v_mov_b32_e32 v86, v0
	v_mov_b32_e32 v87, v0
	v_mov_b32_e32 v88, v0
	v_mov_b32_e32 v89, v0
	v_mov_b32_e32 v90, v0
	v_mov_b32_e32 v91, v0
	v_mov_b32_e32 v92, v0
	v_mov_b32_e32 v93, v0
	v_mov_b32_e32 v94, v0
	v_mov_b32_e32 v95, v0
	s_setprio 1
	v_add_u32_e32 v162, v155, v157
	v_add_u32_e32 v163, v155, v159
	v_add_u32_e32 v164, v155, v160
	v_add_u32_e32 v165, v155, v161
	v_add_u32_e32 v166, v156, v157
	v_add_u32_e32 v167, v156, v159
	v_add_u32_e32 v168, v156, v160
	v_add_u32_e32 v169, v156, v161
	v_add_u32_e32 v170, v158, v157
	v_add_u32_e32 v171, v158, v159
	v_add_u32_e32 v172, v158, v160
	v_add_u32_e32 v173, v158, v161
	v_lshl_add_u64 v[252:253], v[102:103], 0, v[100:101]
	v_lshl_add_u64 v[254:255], v[104:105], 0, v[100:101]
	v_readfirstlane_b32 s100, v124
	s_mov_b64 s[0:1], 0x80
	s_waitcnt vmcnt(0) lgkmcnt(0)
	s_barrier
	s_add_u32 m0, s100, 0x6000
	v_lshl_add_u64 v[106:107], v[252:253], 0, s[96:97]
	global_load_lds_dwordx4 v[106:107], off
	s_add_u32 m0, s100, 0x7000
	v_lshl_add_u64 v[106:107], v[252:253], 0, s[50:51]
	global_load_lds_dwordx4 v[106:107], off
	s_add_u32 m0, s100, 0x8000
	v_lshl_add_u64 v[106:107], v[252:253], 0, s[24:25]
	global_load_lds_dwordx4 v[106:107], off
	s_add_u32 m0, s100, 0x9000
	v_lshl_add_u64 v[106:107], v[252:253], 0, s[26:27]
	global_load_lds_dwordx4 v[106:107], off
	s_add_u32 m0, s100, 0xa000
	v_lshl_add_u64 v[106:107], v[252:253], 0, s[28:29]
	global_load_lds_dwordx4 v[106:107], off
	s_add_u32 m0, s100, 0xb000
	v_lshl_add_u64 v[106:107], v[252:253], 0, s[30:31]
	global_load_lds_dwordx4 v[106:107], off
	v_lshl_add_u64 v[252:253], v[252:253], 0, s[0:1]
	s_mov_b64 s[16:17], 0xb00080
	s_add_u32 m0, s100, 0x10000
	v_lshl_add_u64 v[106:107], v[254:255], 0, s[16:17]
	global_load_lds_dwordx4 v[106:107], off
	s_mov_b64 s[16:17], 0xb10080
	s_add_u32 m0, s100, 0x11000
	v_lshl_add_u64 v[106:107], v[254:255], 0, s[16:17]
	global_load_lds_dwordx4 v[106:107], off
	s_mov_b64 s[16:17], 0xb20080
	s_add_u32 m0, s100, 0x12000
	v_lshl_add_u64 v[106:107], v[254:255], 0, s[16:17]
	global_load_lds_dwordx4 v[106:107], off
	s_mov_b64 s[16:17], 0xb30080
	s_add_u32 m0, s100, 0x13000
	v_lshl_add_u64 v[106:107], v[254:255], 0, s[16:17]
	global_load_lds_dwordx4 v[106:107], off
	v_lshl_add_u64 v[254:255], v[254:255], 0, s[0:1]
	ds_read_b128 v[236:239], v166 offset:49152
	ds_read_b128 v[240:243], v166 offset:53248
	ds_read_b128 v[224:227], v162
	ds_read_b128 v[228:231], v162 offset:4096
	s_mov_b32 s101, 0

; template <int EPI, int MI>
; DI void gemm_tile(const GemmDesc& g, int tm, int tn, char* smem) {
;     ...
;   const int m0 = tm * BM, n0 = tn * 128;
;   const int nk = g.K >> 6;
;   f32x16 acc[MI][2];
; #pragma unroll
;   for (int a = 0; a < MI; ++a)
; #pragma unroll
;     for (int b = 0; b < 2; ++b)
; #pragma unroll
;       for (int i = 0; i < 16; ++i) acc[a][b][i] = 0.f;
;   const int srow = tid >> 3;
;   const int schunk = (tid & 7) ^ ((srow & 7) ^ ((srow >> 3) & 3));
;     ...
;   const int rowA = wm * (32 * MI) + r, rowB = wn * 64 + r;
;   const int hk = hh ^ ((r & 7) ^ ((r >> 3) & 3));
;     ...
;   G_GLDS(0, 0);
;   asm volatile("s_waitcnt vmcnt(0)" ::: "memory");
;   __syncthreads();
;   for (int kt = 0; kt < nk; kt += 2) {
;     if (kt + 1 < nk) G_GLDS(kt + 1, 1);
; template <int EPI, int MI>
; DI void gemm_phase(const GemmDesc& g, char* smem, int vb, int nvb) {
;     ...
;   for (int q = start; q < local; q += step) {
;     const int mg = q / per;
;     const int rem = q - mg * per;
;     const int tn = rem / PM;
;     const int tm = mbase + mg * PM + (rem - tn * PM);
.LBB0_1478:
	s_abs_i32 s0, s44
	s_mul_hi_u32 s1, s0, s42
	s_mul_i32 s4, s1, s38
	s_sub_i32 s0, s0, s4
	s_ashr_i32 s18, s44, 31
	s_add_i32 s4, s1, 1
	s_sub_i32 s5, s0, s38
	s_cmp_ge_u32 s0, s38
	s_cselect_b32 s1, s4, s1
	s_cselect_b32 s0, s5, s0
	s_add_i32 s4, s1, 1
	s_cmp_ge_u32 s0, s38
	s_cselect_b32 s0, s4, s1
	s_xor_b32 s19, s0, s18
	s_sub_i32 s0, s19, s18
	s_mul_i32 s1, s0, s38
	s_sub_i32 s1, s44, s1
	s_abs_i32 s4, s1
	s_mul_hi_u32 s5, s4, s16
	s_mul_i32 s45, s5, s15
	s_sub_i32 s4, s4, s45
	s_ashr_i32 s46, s1, 31
	s_add_i32 s45, s5, 1
	s_sub_i32 s47, s4, s15
	s_cmp_ge_u32 s4, s15
	s_cselect_b32 s5, s45, s5
	s_cselect_b32 s4, s47, s4
	s_add_i32 s45, s5, 1
	s_cmp_ge_u32 s4, s15
	s_cselect_b32 s4, s45, s5
	s_xor_b32 s47, s4, s46
	s_sub_i32 s4, s47, s46
	v_mov_b32_e32 v75, v132
	s_mul_i32 s0, s0, s15
	s_mul_i32 s5, s4, s15
	s_add_i32 s0, s0, s39
	v_ashrrev_i32_e32 v6, 3, v75
	s_sub_i32 s1, s1, s5
	v_bfe_u32 v1, v75, 6, 2
	v_xor_b32_e32 v2, v6, v75
	s_add_i32 s1, s0, s1
	s_lshl_b32 s0, s4, 7
	v_and_b32_e32 v0, 7, v75
	v_bitop3_b32 v2, v2, v1, 7 bitop3:0x6c
	v_lshrrev_b32_e32 v1, 3, v75
	v_readlane_b32 s4, v221, 5
	s_lshl_b32 s45, s1, 7
	v_bfe_u32 v77, v75, 5, 1
	v_bitop3_b32 v0, v1, v0, 3 bitop3:0x6c
	v_readlane_b32 s5, v221, 6
	v_xor_b32_e32 v7, v0, v77
	v_add_u32_e32 v3, s45, v6
	v_mov_b64_e32 v[0:1], s[4:5]
	s_movk_i32 s52, 0x1600
	v_mad_i64_i32 v[0:1], s[4:5], v3, s52, v[0:1]
	v_readlane_b32 s4, v220, 56
	v_readlane_b32 s5, v220, 57
	v_lshlrev_b32_e32 v64, 4, v2
	v_add_u32_e32 v8, s0, v6
	v_mov_b64_e32 v[2:3], s[4:5]
	v_lshlrev_b32_e32 v4, 4, v75
	v_mad_i64_i32 v[2:3], s[4:5], v8, s52, v[2:3]
	v_add_u32_e32 v78, 0, v4
	v_mov_b32_e32 v65, v96
	v_readfirstlane_b32 s4, v78
	v_add_u32_e32 v79, 0x1000, v78
	v_lshl_add_u64 v[0:1], v[0:1], 0, v[64:65]
	s_mov_b32 m0, s4
	s_mov_b64 s[72:73], 0x2c000
	v_readfirstlane_b32 s4, v79
	v_add_u32_e32 v80, 0x2000, v78
	global_load_lds_dwordx4 v[0:1], off
	v_lshl_add_u64 v[4:5], v[0:1], 0, s[72:73]
	s_mov_b32 m0, s4
	s_mov_b64 s[74:75], 0x58000
	v_readfirstlane_b32 s4, v80
	v_add_u32_e32 v81, 0x3000, v78
	global_load_lds_dwordx4 v[4:5], off
	v_lshl_add_u64 v[4:5], v[0:1], 0, s[74:75]
	s_mov_b32 m0, s4
	s_mov_b64 s[76:77], 0x84000
	v_readfirstlane_b32 s4, v81
	v_add_u32_e32 v82, 0x8000, v78
	global_load_lds_dwordx4 v[4:5], off
	v_lshl_add_u64 v[0:1], v[0:1], 0, s[76:77]
	s_mov_b32 m0, s4
	v_readfirstlane_b32 s4, v82
	v_add_u32_e32 v83, 0x9000, v78
	global_load_lds_dwordx4 v[0:1], off
	v_lshl_add_u64 v[0:1], v[2:3], 0, v[64:65]
	s_mov_b32 m0, s4
	v_readfirstlane_b32 s4, v83
	v_add_u32_e32 v84, 0xa000, v78
	global_load_lds_dwordx4 v[0:1], off
	v_lshl_add_u64 v[2:3], v[0:1], 0, s[72:73]
	s_mov_b32 m0, s4
	v_readfirstlane_b32 s4, v84
	v_add_u32_e32 v85, 0xb000, v78
	global_load_lds_dwordx4 v[2:3], off
	v_lshl_add_u64 v[2:3], v[0:1], 0, s[74:75]
	s_mov_b32 m0, s4
	v_readfirstlane_b32 s4, v85
	global_load_lds_dwordx4 v[2:3], off
	v_lshl_add_u64 v[0:1], v[0:1], 0, s[76:77]
	s_mov_b32 m0, s4
	s_mul_i32 s18, s18, 7
	global_load_lds_dwordx4 v[0:1], off
	v_and_b32_e32 v74, 31, v75
	s_add_i32 s46, s46, s18
	v_ashrrev_i32_e32 v76, 7, v75
	v_lshlrev_b32_e32 v0, 7, v74
	s_sub_i32 s4, s46, s47
	s_mul_i32 s19, s19, 7
	v_lshl_or_b32 v0, v76, 13, v0
	s_sub_i32 s4, s4, s19
	v_add_u32_e32 v86, 0, v0
	v_lshlrev_b32_e32 v0, 7, v75
	s_mul_i32 s4, s43, s4
	v_and_b32_e32 v0, 0x2f80, v0
	s_add_i32 s4, s4, s17
	s_waitcnt vmcnt(0)
	v_add_u32_e32 v87, 0, v0
	v_add_u32_e32 v2, s4, v6
	v_mov_b64_e32 v[0:1], s[70:71]
	s_waitcnt vmcnt(0)
	v_lshlrev_b32_e32 v88, 4, v7
	v_mad_i64_i32 v[66:67], s[4:5], v2, s52, v[0:1]
	v_mad_i64_i32 v[68:69], s[4:5], v8, s52, v[0:1]
	v_mov_b32_e32 v0, 0
	v_xor_b32_e32 v89, 32, v88
	v_xor_b32_e32 v90, 64, v88
	v_xor_b32_e32 v91, 0x60, v88
	s_mov_b32 s18, 0
	v_mov_b32_e32 v1, v0
	v_mov_b32_e32 v2, v0
	v_mov_b32_e32 v3, v0
	v_mov_b32_e32 v4, v0
	v_mov_b32_e32 v5, v0
	v_mov_b32_e32 v6, v0
	v_mov_b32_e32 v7, v0
	v_mov_b32_e32 v8, v0
	v_mov_b32_e32 v9, v0
	v_mov_b32_e32 v10, v0
	v_mov_b32_e32 v11, v0
	v_mov_b32_e32 v12, v0
	v_mov_b32_e32 v13, v0
	v_mov_b32_e32 v14, v0
	v_mov_b32_e32 v15, v0
	v_mov_b32_e32 v16, v0
	v_mov_b32_e32 v17, v0
	v_mov_b32_e32 v18, v0
	v_mov_b32_e32 v19, v0
	v_mov_b32_e32 v20, v0
	v_mov_b32_e32 v21, v0
	v_mov_b32_e32 v22, v0
	v_mov_b32_e32 v23, v0
	v_mov_b32_e32 v24, v0
	v_mov_b32_e32 v25, v0
	v_mov_b32_e32 v26, v0
	v_mov_b32_e32 v27, v0
	v_mov_b32_e32 v28, v0
	v_mov_b32_e32 v29, v0
	v_mov_b32_e32 v30, v0
	v_mov_b32_e32 v31, v0
	v_mov_b32_e32 v32, v0
	v_mov_b32_e32 v33, v0
	v_mov_b32_e32 v34, v0
	v_mov_b32_e32 v35, v0
	v_mov_b32_e32 v36, v0
	v_mov_b32_e32 v37, v0
	v_mov_b32_e32 v38, v0
	v_mov_b32_e32 v39, v0
	v_mov_b32_e32 v40, v0
	v_mov_b32_e32 v41, v0
	v_mov_b32_e32 v42, v0
	v_mov_b32_e32 v43, v0
	v_mov_b32_e32 v44, v0
	v_mov_b32_e32 v45, v0
	v_mov_b32_e32 v46, v0
	v_mov_b32_e32 v47, v0
	v_mov_b32_e32 v48, v0
	v_mov_b32_e32 v49, v0
	v_mov_b32_e32 v50, v0
	v_mov_b32_e32 v51, v0
	v_mov_b32_e32 v52, v0
	v_mov_b32_e32 v53, v0
	v_mov_b32_e32 v54, v0
	v_mov_b32_e32 v55, v0
	v_mov_b32_e32 v56, v0
	v_mov_b32_e32 v57, v0
	v_mov_b32_e32 v58, v0
	v_mov_b32_e32 v59, v0
	v_mov_b32_e32 v60, v0
	v_mov_b32_e32 v61, v0
	v_mov_b32_e32 v62, v0
	v_mov_b32_e32 v63, v0
	s_setprio 1
	v_add_u32_e32 v92, v86, v88
	v_add_u32_e32 v93, v86, v89
	v_add_u32_e32 v94, v86, v90
	v_add_u32_e32 v95, v86, v91
	v_add_u32_e32 v97, v87, v88
	v_add_u32_e32 v98, v87, v89
	v_add_u32_e32 v99, v87, v90
	v_add_u32_e32 v100, v87, v91
	v_lshl_add_u64 v[104:105], v[66:67], 0, v[64:65]
	v_lshl_add_u64 v[106:107], v[68:69], 0, v[64:65]
	v_readfirstlane_b32 s100, v78
	s_mov_b64 s[46:47], 0x80
	s_waitcnt vmcnt(0) lgkmcnt(0)
	s_barrier
	s_mov_b64 s[4:5], 0x5872080
	s_add_u32 m0, s100, 0x4000
	v_lshl_add_u64 v[102:103], v[104:105], 0, s[4:5]
	global_load_lds_dwordx4 v[102:103], off
	s_mov_b64 s[4:5], 0x589e080
	s_add_u32 m0, s100, 0x5000
	v_lshl_add_u64 v[102:103], v[104:105], 0, s[4:5]
	global_load_lds_dwordx4 v[102:103], off
	s_mov_b64 s[4:5], 0x58ca080
	s_add_u32 m0, s100, 0x6000
	v_lshl_add_u64 v[102:103], v[104:105], 0, s[4:5]
	global_load_lds_dwordx4 v[102:103], off
	s_mov_b64 s[4:5], 0x58f6080
	s_add_u32 m0, s100, 0x7000
	v_lshl_add_u64 v[102:103], v[104:105], 0, s[4:5]
	global_load_lds_dwordx4 v[102:103], off
	v_lshl_add_u64 v[104:105], v[104:105], 0, s[46:47]
	ds_read_b128 v[240:243], v97 offset:32768
	ds_read_b128 v[244:247], v97 offset:36864
	ds_read_b128 v[224:227], v92
	ds_read_b128 v[228:231], v92 offset:4096
	s_mov_b32 s101, 0

; template <int EPI, int MI>
; DI void gemm_tile(const GemmDesc& g, int tm, int tn, char* smem) {
;     ...
;   const int srow = tid >> 3;
;   const int schunk = (tid & 7) ^ ((srow & 7) ^ ((srow >> 3) & 3));
; template <int EPI, int MI>
; DI void gemm_phase(const GemmDesc& g, char* smem, int vb, int nvb) {
;     ...
;   for (int q = start; q < local; q += step) {
;     const int mg = q / per;
;     const int rem = q - mg * per;
;     const int tn = rem / PM;
;     const int tm = mbase + mg * PM + (rem - tn * PM);
.LBB0_1491:
	s_abs_i32 s0, s40
	v_readlane_b32 s1, v219, 48
	s_mul_hi_u32 s1, s0, s1
	v_readlane_b32 s17, v219, 47
	s_mul_i32 s4, s1, s17
	s_sub_i32 s0, s0, s4
	s_ashr_i32 s15, s40, 31
	s_add_i32 s4, s1, 1
	s_sub_i32 s5, s0, s17
	s_cmp_ge_u32 s0, s17
	s_cselect_b32 s1, s4, s1
	s_cselect_b32 s0, s5, s0
	s_add_i32 s4, s1, 1
	s_cmp_ge_u32 s0, s17
	s_cselect_b32 s0, s4, s1
	s_xor_b32 s16, s0, s15
	s_sub_i32 s0, s16, s15
	s_mul_i32 s1, s0, s17
	s_sub_i32 s1, s40, s1
	s_abs_i32 s4, s1
	v_readlane_b32 s5, v219, 46
	s_mul_hi_u32 s5, s4, s5
	v_readlane_b32 s41, v218, 32
	s_mul_i32 s18, s5, s41
	s_sub_i32 s4, s4, s18
	s_ashr_i32 s17, s1, 31
	s_add_i32 s18, s5, 1
	s_sub_i32 s19, s4, s41
	s_cmp_ge_u32 s4, s41
	s_cselect_b32 s5, s18, s5
	s_cselect_b32 s4, s19, s4
	s_add_i32 s18, s5, 1
	s_cmp_ge_u32 s4, s41
	s_cselect_b32 s4, s18, s5
	s_xor_b32 s18, s4, s17
	v_mov_b32_e32 v97, v132
	s_sub_i32 s4, s18, s17
	s_mul_i32 s0, s0, s41
	v_ashrrev_i32_e32 v6, 3, v97
	s_mul_i32 s5, s4, s41
	s_waitcnt vmcnt(8)
	v_ashrrev_i32_e32 v109, 7, v97
	v_bfe_u32 v1, v97, 6, 2
	v_xor_b32_e32 v2, v6, v97
	s_add_i32 s0, s0, s54
	s_sub_i32 s1, s1, s5
	v_and_b32_e32 v108, 31, v97
	v_bitop3_b32 v2, v2, v1, 7 bitop3:0x6c
	v_mul_lo_u32 v1, v109, s6
	s_add_i32 s1, s0, s1
	s_lshl_b32 s0, s4, 7
	v_and_b32_e32 v0, 7, v97
	v_or_b32_e32 v7, v1, v108
	v_lshrrev_b32_e32 v1, 3, v97
	v_readlane_b32 s4, v221, 5
	s_mul_i32 s41, s1, 0xc0
	v_bfe_u32 v115, v97, 5, 1
	v_bitop3_b32 v0, v1, v0, 3 bitop3:0x6c
	v_readlane_b32 s5, v221, 6
	v_xor_b32_e32 v8, v0, v115
	v_add_u32_e32 v3, s41, v6
	v_mov_b64_e32 v[0:1], s[4:5]
	s_movk_i32 s19, 0x1600
	v_mad_i64_i32 v[0:1], s[4:5], v3, s19, v[0:1]
	v_readlane_b32 s4, v220, 56
	v_readlane_b32 s5, v220, 57
	v_lshlrev_b32_e32 v98, 4, v2
	v_add_u32_e32 v9, s0, v6
	v_mov_b64_e32 v[2:3], s[4:5]
	v_lshlrev_b32_e32 v120, 4, v97
	v_mad_i64_i32 v[2:3], s[4:5], v9, s19, v[2:3]
	v_add_u32_e32 v121, 0, v120
	v_mov_b32_e32 v99, v96
	v_readfirstlane_b32 s4, v121
	v_add_u32_e32 v122, 0x1000, v121
	v_lshl_add_u64 v[0:1], v[0:1], 0, v[98:99]
	s_mov_b32 m0, s4
	s_mov_b64 s[42:43], 0x2c000
	v_readfirstlane_b32 s4, v122
	v_add_u32_e32 v123, 0x2000, v121
	global_load_lds_dwordx4 v[0:1], off
	v_lshl_add_u64 v[4:5], v[0:1], 0, s[42:43]
	s_mov_b32 m0, s4
	s_mov_b64 s[44:45], 0x58000
	v_readfirstlane_b32 s4, v123
	v_add_u32_e32 v124, 0x3000, v121
	global_load_lds_dwordx4 v[4:5], off
	v_lshl_add_u64 v[4:5], v[0:1], 0, s[44:45]
	s_mov_b32 m0, s4
	s_mov_b64 s[46:47], 0x84000
	v_readfirstlane_b32 s4, v124
	global_load_lds_dwordx4 v[4:5], off
	v_lshl_add_u64 v[4:5], v[0:1], 0, s[46:47]
	s_mov_b32 m0, s4
	s_mov_b64 s[4:5], 0xb0000
	v_add_u32_e32 v125, 0x4000, v121
	global_load_lds_dwordx4 v[4:5], off
	v_lshl_add_u64 v[4:5], v[0:1], 0, s[4:5]
	v_readfirstlane_b32 s4, v125
	s_mov_b32 m0, s4
	s_mov_b64 s[4:5], 0xdc000
	v_add_u32_e32 v126, 0x5000, v121
	v_lshl_add_u64 v[0:1], v[0:1], 0, s[4:5]
	v_readfirstlane_b32 s4, v126
	v_add_u32_e32 v127, 0xc000, v121
	global_load_lds_dwordx4 v[4:5], off
	s_mov_b32 m0, s4
	v_readfirstlane_b32 s4, v127
	v_add_u32_e32 v128, 0xd000, v121
	global_load_lds_dwordx4 v[0:1], off
	v_lshl_add_u64 v[0:1], v[2:3], 0, v[98:99]
	s_mov_b32 m0, s4
	v_readfirstlane_b32 s4, v128
	v_add_u32_e32 v129, 0xe000, v121
	global_load_lds_dwordx4 v[0:1], off
	v_lshl_add_u64 v[2:3], v[0:1], 0, s[42:43]
	s_mov_b32 m0, s4
	v_readfirstlane_b32 s4, v129
	v_add_u32_e32 v130, 0xf000, v121
	global_load_lds_dwordx4 v[2:3], off
	v_lshl_add_u64 v[2:3], v[0:1], 0, s[44:45]
	s_mov_b32 m0, s4
	v_readfirstlane_b32 s4, v130
	global_load_lds_dwordx4 v[2:3], off
	v_lshl_add_u64 v[0:1], v[0:1], 0, s[46:47]
	s_mov_b32 m0, s4
	s_mul_i32 s15, s15, 7
	global_load_lds_dwordx4 v[0:1], off
	s_add_i32 s17, s17, s15
	s_sub_i32 s4, s17, s18
	s_mul_i32 s16, s16, 7
	s_sub_i32 s4, s4, s16
	v_readlane_b32 s5, v218, 33
	v_lshlrev_b32_e32 v0, 7, v97
	s_mul_i32 s4, s5, s4
	v_and_b32_e32 v0, 0x2f80, v0
	s_add_i32 s4, s4, s39
	s_waitcnt vmcnt(0)
; template <int EPI, int MI>
; DI void gemm_tile(const GemmDesc& g, int tm, int tn, char* smem) {
;     ...
;   f32x16 acc[MI][2];
; #pragma unroll
;   for (int a = 0; a < MI; ++a)
; #pragma unroll
;     for (int b = 0; b < 2; ++b)
; #pragma unroll
;       for (int i = 0; i < 16; ++i) acc[a][b][i] = 0.f;
;   const int srow = tid >> 3;
;   const int schunk = (tid & 7) ^ ((srow & 7) ^ ((srow >> 3) & 3));
;     ...
;   const int rowA = wm * (32 * MI) + r, rowB = wn * 64 + r;
;   const int hk = hh ^ ((r & 7) ^ ((r >> 3) & 3));
;     ...
;   G_GLDS(0, 0);
;   asm volatile("s_waitcnt vmcnt(0)" ::: "memory");
;   __syncthreads();
	v_add_u32_e32 v153, 0, v0
	v_add_u32_e32 v155, s10, v0
	v_add_u32_e32 v2, s4, v6
	v_mov_b64_e32 v[0:1], s[70:71]
	v_lshlrev_b32_e32 v154, 4, v8
	v_mad_i64_i32 v[100:101], s[4:5], v2, s19, v[0:1]
	v_mad_i64_i32 v[102:103], s[4:5], v9, s19, v[0:1]
	v_mov_b32_e32 v0, 0
	v_lshl_add_u32 v131, v7, 7, 0
	v_xor_b32_e32 v156, 32, v154
	v_xor_b32_e32 v157, 64, v154
	v_xor_b32_e32 v158, 0x60, v154
	s_mov_b32 s15, 0
	v_mov_b32_e32 v1, v0
	v_mov_b32_e32 v2, v0
	v_mov_b32_e32 v3, v0
	v_mov_b32_e32 v4, v0
	v_mov_b32_e32 v5, v0
	v_mov_b32_e32 v6, v0
	v_mov_b32_e32 v7, v0
	v_mov_b32_e32 v8, v0
	v_mov_b32_e32 v9, v0
	v_mov_b32_e32 v10, v0
	v_mov_b32_e32 v11, v0
	v_mov_b32_e32 v12, v0
	v_mov_b32_e32 v13, v0
	v_mov_b32_e32 v14, v0
	v_mov_b32_e32 v15, v0
	v_mov_b32_e32 v16, v0
	v_mov_b32_e32 v17, v0
	v_mov_b32_e32 v18, v0
	v_mov_b32_e32 v19, v0
	v_mov_b32_e32 v20, v0
	v_mov_b32_e32 v21, v0
	v_mov_b32_e32 v22, v0
	v_mov_b32_e32 v23, v0
	v_mov_b32_e32 v24, v0
	v_mov_b32_e32 v25, v0
	v_mov_b32_e32 v26, v0
	v_mov_b32_e32 v27, v0
	v_mov_b32_e32 v28, v0
	v_mov_b32_e32 v29, v0
	v_mov_b32_e32 v30, v0
	v_mov_b32_e32 v31, v0
	v_mov_b32_e32 v32, v0
	v_mov_b32_e32 v33, v0
	v_mov_b32_e32 v34, v0
	v_mov_b32_e32 v35, v0
	v_mov_b32_e32 v36, v0
	v_mov_b32_e32 v37, v0
	v_mov_b32_e32 v38, v0
	v_mov_b32_e32 v39, v0
	v_mov_b32_e32 v40, v0
	v_mov_b32_e32 v41, v0
	v_mov_b32_e32 v42, v0
	v_mov_b32_e32 v43, v0
	v_mov_b32_e32 v44, v0
	v_mov_b32_e32 v45, v0
	v_mov_b32_e32 v46, v0
	v_mov_b32_e32 v47, v0
	v_mov_b32_e32 v48, v0
	s_waitcnt vmcnt(0)
	v_mov_b32_e32 v49, v0
	v_mov_b32_e32 v50, v0
	v_mov_b32_e32 v51, v0
	v_mov_b32_e32 v52, v0
	v_mov_b32_e32 v53, v0
	v_mov_b32_e32 v54, v0
	v_mov_b32_e32 v55, v0
	v_mov_b32_e32 v56, v0
	v_mov_b32_e32 v57, v0
	v_mov_b32_e32 v58, v0
	v_mov_b32_e32 v59, v0
	v_mov_b32_e32 v60, v0
	v_mov_b32_e32 v61, v0
	v_mov_b32_e32 v62, v0
	v_mov_b32_e32 v63, v0
	v_mov_b32_e32 v64, v0
	v_mov_b32_e32 v65, v0
	v_mov_b32_e32 v66, v0
	v_mov_b32_e32 v67, v0
	v_mov_b32_e32 v68, v0
	v_mov_b32_e32 v69, v0
	v_mov_b32_e32 v70, v0
	v_mov_b32_e32 v71, v0
	v_mov_b32_e32 v72, v0
	v_mov_b32_e32 v73, v0
	v_mov_b32_e32 v74, v0
	v_mov_b32_e32 v75, v0
	v_mov_b32_e32 v76, v0
	v_mov_b32_e32 v77, v0
	v_mov_b32_e32 v78, v0
	v_mov_b32_e32 v79, v0
	v_mov_b32_e32 v80, v0
	v_mov_b32_e32 v81, v0
	v_mov_b32_e32 v82, v0
	v_mov_b32_e32 v83, v0
	v_mov_b32_e32 v84, v0
	v_mov_b32_e32 v85, v0
	v_mov_b32_e32 v86, v0
	v_mov_b32_e32 v87, v0
	v_mov_b32_e32 v88, v0
	v_mov_b32_e32 v89, v0
	v_mov_b32_e32 v90, v0
	v_mov_b32_e32 v91, v0
	v_mov_b32_e32 v92, v0
	v_mov_b32_e32 v93, v0
	v_mov_b32_e32 v94, v0
	v_mov_b32_e32 v95, v0
	s_setprio 1
	v_add_u32_e32 v162, v131, v154
	v_add_u32_e32 v163, v131, v156
	v_add_u32_e32 v164, v131, v157
	v_add_u32_e32 v165, v131, v158
	v_add_u32_e32 v166, v153, v154
	v_add_u32_e32 v167, v153, v156
	v_add_u32_e32 v168, v153, v157
	v_add_u32_e32 v169, v153, v158
	v_add_u32_e32 v170, v155, v154
	v_add_u32_e32 v171, v155, v156
	v_add_u32_e32 v172, v155, v157
	v_add_u32_e32 v173, v155, v158
	v_lshl_add_u64 v[252:253], v[100:101], 0, v[98:99]
	v_lshl_add_u64 v[254:255], v[102:103], 0, v[98:99]
	v_readfirstlane_b32 s100, v121
	s_mov_b64 s[4:5], 0x80
	s_waitcnt vmcnt(0) lgkmcnt(0)
	s_barrier
	s_mov_b64 s[16:17], 0x5872080
	s_add_u32 m0, s100, 0x6000
	v_lshl_add_u64 v[106:107], v[252:253], 0, s[16:17]
	global_load_lds_dwordx4 v[106:107], off
	s_mov_b64 s[16:17], 0x589e080
	s_add_u32 m0, s100, 0x7000
	v_lshl_add_u64 v[106:107], v[252:253], 0, s[16:17]
	global_load_lds_dwordx4 v[106:107], off
	s_mov_b64 s[16:17], 0x58ca080
	s_add_u32 m0, s100, 0x8000
	v_lshl_add_u64 v[106:107], v[252:253], 0, s[16:17]
	global_load_lds_dwordx4 v[106:107], off
	s_mov_b64 s[16:17], 0x58f6080
	s_add_u32 m0, s100, 0x9000
	v_lshl_add_u64 v[106:107], v[252:253], 0, s[16:17]
	global_load_lds_dwordx4 v[106:107], off
	s_mov_b64 s[16:17], 0x5922080
	s_add_u32 m0, s100, 0xa000
	v_lshl_add_u64 v[106:107], v[252:253], 0, s[16:17]
	global_load_lds_dwordx4 v[106:107], off
	s_mov_b64 s[16:17], 0x594e080
	s_add_u32 m0, s100, 0xb000
	v_lshl_add_u64 v[106:107], v[252:253], 0, s[16:17]
	global_load_lds_dwordx4 v[106:107], off
	v_lshl_add_u64 v[252:253], v[252:253], 0, s[4:5]
	s_mov_b64 s[16:17], 0x1b80080
	s_add_u32 m0, s100, 0x10000
	v_lshl_add_u64 v[106:107], v[254:255], 0, s[16:17]
	global_load_lds_dwordx4 v[106:107], off
	s_mov_b64 s[16:17], 0x1bac080
	s_add_u32 m0, s100, 0x11000
	v_lshl_add_u64 v[106:107], v[254:255], 0, s[16:17]
	global_load_lds_dwordx4 v[106:107], off
	s_mov_b64 s[16:17], 0x1bd8080
	s_add_u32 m0, s100, 0x12000
	v_lshl_add_u64 v[106:107], v[254:255], 0, s[16:17]
	global_load_lds_dwordx4 v[106:107], off
	s_mov_b64 s[16:17], 0x1c04080
	s_add_u32 m0, s100, 0x13000
	v_lshl_add_u64 v[106:107], v[254:255], 0, s[16:17]
	global_load_lds_dwordx4 v[106:107], off
	v_lshl_add_u64 v[254:255], v[254:255], 0, s[4:5]
	ds_read_b128 v[236:239], v166 offset:49152
	ds_read_b128 v[240:243], v166 offset:53248
	ds_read_b128 v[224:227], v162
	ds_read_b128 v[228:231], v162 offset:4096
	s_mov_b32 s15, 0
